# UP-projection conv/SiLU epilogue rewritten by hand: DPP-fused FMAs for the causal conv3, folded exp2 constants, 32-bit store addressing
# speedup vs baseline: 1.0156x; 1.0093x over previous
;     __device__ __forceinline__ void operator()(const Acc& acc, const Unit& u, int wr, int wc, int fr, int fq, LAS unsigned char* lds, f32x4 epar) const {
;     ...
;         LAS float* pw = (LAS float*)(lds + STAGE_BYTES + 64 + (wr * 4 + wc) * 1024);
;         *(LAS f32x4*)(pw + (fq * 16 + fr) * 4) = epar;
;         asm volatile("s_waitcnt lgkmcnt(0)" ::: "memory");
;         float w0[NV], w1[NV], w2[NV], bb[NV];
; #pragma unroll
;         for (int i = 0; i < NV; i += 4) { const f32x4 a = *(const LAS f32x4*)(pw + NV * fq + i), b = *(const LAS f32x4*)(pw + 32 + NV * fq + i), c = *(const LAS f32x4*)(pw + 64 + NV * fq + i);
;             f32x4 d = (f32x4){0.f, 0.f, 0.f, 0.f}; if (MODE == 0) d = *(const LAS f32x4*)(pw + 96 + NV * fq + i);
; #pragma unroll
;             for (int j = 0; j < 4; ++j) { w0[i + j] = a[j]; w1[i + j] = b[j]; w2[i + j] = c[j]; bb[i + j] = d[j]; } }
;         float sq[2][4];
; #pragma unroll
;         for (int ai = 0; ai < 2; ++ai)
; #pragma unroll
;             for (int m = 0; m < 4; ++m) sq[ai][m] = pw[128 + ai * 64 + m * 16 + fr];
; #pragma unroll
;         for (int ai = 0; ai < 2; ++ai) {
;             const int strip = u.pm * 4 + ai * 2 + wr;
;             float p1prev[NV], p2prev[NV];
; #pragma unroll
;             for (int i = 0; i < NV; ++i) { p1prev[i] = 0.f; p2prev[i] = 0.f; }
; #pragma unroll
;             for (int m = 0; m < 4; ++m) {
;                 const int r = u.pm * BM + ai * HALF + wr * 64 + m * 16 + fr;
;                 const float rs = __builtin_amdgcn_rsqf(sq[ai][m] * (1.0f / DM) + RMS_EPS);
;                 float X[NV], Y[NV], o[NV];
;                 if (MODE == 0) {
; #pragma unroll
;                     for (int n = 0; n < 2; ++n)
; #pragma unroll
;                         for (int j = 0; j < 4; ++j) { X[n * 4 + j] = acc[ai][0][m][n][j] * rs; Y[n * 4 + j] = acc[ai][1][m][n][j] * rs; }
;                 } else {
; #pragma unroll
;                     for (int j = 0; j < 4; ++j) { X[j] = (acc[ai][0][m][1][j] * rs) * (acc[ai][1][m][0][j] * rs); Y[j] = acc[ai][0][m][0][j] * rs; }
;                 }
; #pragma unroll
;                 for (int i = 0; i < NV; ++i) {
;                     const float a1 = dpp_rot<0x121>(X[i]), a2 = dpp_rot<0x122>(X[i]);
;                     const float q1 = fr >= 1 ? a1 : p1prev[i], q2 = fr >= 2 ? a2 : p2prev[i];
;                     p1prev[i] = a1; p2prev[i] = a2;
.LBB0_692:
	ds_write_b128 v198, v[72:75]
	s_mov_b64 s[24:25], exec
	s_waitcnt lgkmcnt(0)
	ds_read_b128 v[88:91], v199
	ds_read_b128 v[92:95], v199 offset:16
	ds_read_b128 v[128:131], v199 offset:128
	ds_read_b128 v[132:135], v199 offset:144
	ds_read_b128 v[136:139], v199 offset:256
	ds_read_b128 v[140:143], v199 offset:272
	ds_read_b128 v[174:177], v199 offset:384
	ds_read_b128 v[178:181], v199 offset:400
	ds_read2_b32 v[182:183], v191 offset0:128 offset1:144
	ds_read2_b32 v[184:185], v191 offset0:160 offset1:176
	ds_read2_b32 v[76:77], v191 offset0:192 offset1:208
	ds_read2_b32 v[78:79], v191 offset0:224 offset1:240
	v_lshl_add_u32 v230, s70, 8, v190
	v_lshl_or_b32 v231, s72, 7, v192
	v_mul_u32_u24_e32 v230, 0x1600, v230
	s_lshl_b32 s26, s70, 2
	s_add_i32 s26, s26, s14
	s_mul_i32 s16, s26, 6
	v_and_b32_e32 v233, 15, v190
	v_lshl_add_u32 v230, v231, 1, v230
	v_add_u32_e32 v233, s16, v233
	v_mul_u32_u24_e32 v233, 0x1600, v233
	s_nop 0
	v_lshl_add_u32 v233, v231, 1, v233
	s_waitcnt lgkmcnt(0)
	v_mul_f32_e32 v88, 0xbfb8aa3b, v88
	v_mul_f32_e32 v89, 0xbfb8aa3b, v89
	v_mul_f32_e32 v90, 0xbfb8aa3b, v90
	v_mul_f32_e32 v91, 0xbfb8aa3b, v91
	v_mul_f32_e32 v92, 0xbfb8aa3b, v92
	v_mul_f32_e32 v93, 0xbfb8aa3b, v93
	v_mul_f32_e32 v94, 0xbfb8aa3b, v94
	v_mul_f32_e32 v95, 0xbfb8aa3b, v95
	v_mul_f32_e32 v128, 0xbfb8aa3b, v128
	v_mul_f32_e32 v129, 0xbfb8aa3b, v129
	v_mul_f32_e32 v130, 0xbfb8aa3b, v130
	v_mul_f32_e32 v131, 0xbfb8aa3b, v131
	v_mul_f32_e32 v132, 0xbfb8aa3b, v132
	v_mul_f32_e32 v133, 0xbfb8aa3b, v133
	v_mul_f32_e32 v134, 0xbfb8aa3b, v134
	v_mul_f32_e32 v135, 0xbfb8aa3b, v135
	v_mul_f32_e32 v136, 0xbfb8aa3b, v136
	v_mul_f32_e32 v137, 0xbfb8aa3b, v137
	v_mul_f32_e32 v138, 0xbfb8aa3b, v138
	v_mul_f32_e32 v139, 0xbfb8aa3b, v139
	v_mul_f32_e32 v140, 0xbfb8aa3b, v140
	v_mul_f32_e32 v141, 0xbfb8aa3b, v141
	v_mul_f32_e32 v142, 0xbfb8aa3b, v142
	v_mul_f32_e32 v143, 0xbfb8aa3b, v143
	v_mul_f32_e32 v174, 0xbfb8aa3b, v174
	v_mul_f32_e32 v175, 0xbfb8aa3b, v175
	v_mul_f32_e32 v176, 0xbfb8aa3b, v176
	v_mul_f32_e32 v177, 0xbfb8aa3b, v177
	v_mul_f32_e32 v178, 0xbfb8aa3b, v178
	v_mul_f32_e32 v179, 0xbfb8aa3b, v179
	v_mul_f32_e32 v180, 0xbfb8aa3b, v180
	v_mul_f32_e32 v181, 0xbfb8aa3b, v181
	v_fmamk_f32 v182, v182, 0x3a800000, v200
	v_fmamk_f32 v183, v183, 0x3a800000, v200
	v_fmamk_f32 v184, v184, 0x3a800000, v200
	v_fmamk_f32 v185, v185, 0x3a800000, v200
	v_fmamk_f32 v76, v76, 0x3a800000, v200
	v_fmamk_f32 v77, v77, 0x3a800000, v200
	v_fmamk_f32 v78, v78, 0x3a800000, v200
	v_fmamk_f32 v79, v79, 0x3a800000, v200
	v_rsq_f32_e32 v182, v182
	v_rsq_f32_e32 v183, v183
	v_rsq_f32_e32 v184, v184
	v_rsq_f32_e32 v185, v185
	v_rsq_f32_e32 v76, v76
	v_rsq_f32_e32 v77, v77
	v_rsq_f32_e32 v78, v78
	v_rsq_f32_e32 v79, v79
	s_nop 0
	v_mul_f32_e32 v202, 0xbf317218, v182
	v_mul_f32_e32 v203, 0xbf317218, v183
	v_mul_f32_e32 v204, 0xbf317218, v184
	v_mul_f32_e32 v205, 0xbf317218, v185
	v_mul_f32_e32 v206, 0xbf317218, v76
	v_mul_f32_e32 v207, 0xbf317218, v77
	v_mul_f32_e32 v208, 0xbf317218, v78
	v_mul_f32_e32 v209, 0xbf317218, v79
	v_mul_f32_e32 v152, v152, v182
	v_mul_f32_e32 v153, v153, v182
	v_mul_f32_e32 v154, v154, v182
	v_mul_f32_e32 v155, v155, v182
	v_mul_f32_e32 v144, v144, v182
	v_mul_f32_e32 v145, v145, v182
	v_mul_f32_e32 v146, v146, v182
	v_mul_f32_e32 v147, v147, v182
	v_fma_f32 v210, v152, v136, v174
	v_fma_f32 v211, v153, v137, v175
	v_fma_f32 v212, v154, v138, v176
	v_fma_f32 v213, v155, v139, v177
	v_fma_f32 v214, v144, v140, v178
	v_fma_f32 v215, v145, v141, v179
	v_fma_f32 v216, v146, v142, v180
	v_fma_f32 v217, v147, v143, v181
	v_mul_f32_e32 v218, v156, v182
	v_mul_f32_e32 v219, v157, v182
	v_mul_f32_e32 v220, v158, v182
	v_mul_f32_e32 v221, v159, v182
	v_mul_f32_e32 v222, v148, v182
	v_mul_f32_e32 v223, v149, v182
	v_mul_f32_e32 v224, v150, v182
	v_mul_f32_e32 v225, v151, v182
	v_cvt_pk_bf16_f32 v236, v152, v153
	v_cvt_pk_bf16_f32 v237, v154, v155
	v_cvt_pk_bf16_f32 v238, v144, v145
	v_cvt_pk_bf16_f32 v239, v146, v147
	v_cvt_pk_bf16_f32 v240, v218, v219
	v_cvt_pk_bf16_f32 v241, v220, v221
	v_cvt_pk_bf16_f32 v242, v222, v223
	v_cvt_pk_bf16_f32 v243, v224, v225
	v_add_u32_e32 v234, 0x2c00, v233
	v_add_u32_e32 v235, 0x5800, v233
	s_andn2_b64 exec, exec, s[8:9]
	global_store_dwordx4 v234, v[236:239], s[42:43]
	global_store_dwordx4 v235, v[240:243], s[42:43]
	s_mov_b64 exec, s[24:25]
	v_fmac_f32_dpp v210, v152, v128 row_shr:1 row_mask:0xf bank_mask:0xf
	v_fmac_f32_dpp v211, v153, v129 row_shr:1 row_mask:0xf bank_mask:0xf
	v_fmac_f32_dpp v212, v154, v130 row_shr:1 row_mask:0xf bank_mask:0xf
	v_fmac_f32_dpp v213, v155, v131 row_shr:1 row_mask:0xf bank_mask:0xf
	v_fmac_f32_dpp v214, v144, v132 row_shr:1 row_mask:0xf bank_mask:0xf
	v_fmac_f32_dpp v215, v145, v133 row_shr:1 row_mask:0xf bank_mask:0xf
	v_fmac_f32_dpp v216, v146, v134 row_shr:1 row_mask:0xf bank_mask:0xf
	v_fmac_f32_dpp v217, v147, v135 row_shr:1 row_mask:0xf bank_mask:0xf
	v_fmac_f32_dpp v210, v152, v88 row_shr:2 row_mask:0xf bank_mask:0xf
	v_fmac_f32_dpp v211, v153, v89 row_shr:2 row_mask:0xf bank_mask:0xf
	v_fmac_f32_dpp v212, v154, v90 row_shr:2 row_mask:0xf bank_mask:0xf
	v_fmac_f32_dpp v213, v155, v91 row_shr:2 row_mask:0xf bank_mask:0xf
	v_fmac_f32_dpp v214, v144, v92 row_shr:2 row_mask:0xf bank_mask:0xf
	v_fmac_f32_dpp v215, v145, v93 row_shr:2 row_mask:0xf bank_mask:0xf
	v_fmac_f32_dpp v216, v146, v94 row_shr:2 row_mask:0xf bank_mask:0xf
	v_fmac_f32_dpp v217, v147, v95 row_shr:2 row_mask:0xf bank_mask:0xf
	v_exp_f32_e32 v218, v210
	v_exp_f32_e32 v219, v211
	v_exp_f32_e32 v220, v212
	v_exp_f32_e32 v221, v213
	v_exp_f32_e32 v222, v214
	v_exp_f32_e32 v223, v215
	v_exp_f32_e32 v224, v216
;     __device__ __forceinline__ void operator()(const Acc& acc, const Unit& u, int wr, int wc, int fr, int fq, LAS unsigned char* lds, f32x4 epar) const {
;     ...
;             for (int m = 0; m < 4; ++m) {
;                 const int r = u.pm * BM + ai * HALF + wr * 64 + m * 16 + fr;
;                 const float rs = __builtin_amdgcn_rsqf(sq[ai][m] * (1.0f / DM) + RMS_EPS);
;                 float X[NV], Y[NV], o[NV];
;                 if (MODE == 0) {
; #pragma unroll
;                     for (int n = 0; n < 2; ++n)
; #pragma unroll
;                         for (int j = 0; j < 4; ++j) { X[n * 4 + j] = acc[ai][0][m][n][j] * rs; Y[n * 4 + j] = acc[ai][1][m][n][j] * rs; }
;                 } else {
; #pragma unroll
;                     for (int j = 0; j < 4; ++j) { X[j] = (acc[ai][0][m][1][j] * rs) * (acc[ai][1][m][0][j] * rs); Y[j] = acc[ai][0][m][0][j] * rs; }
;                 }
; #pragma unroll
;                 for (int i = 0; i < NV; ++i) {
;                     const float a1 = dpp_rot<0x121>(X[i]), a2 = dpp_rot<0x122>(X[i]);
;                     const float q1 = fr >= 1 ? a1 : p1prev[i], q2 = fr >= 2 ? a2 : p2prev[i];
;                     p1prev[i] = a1; p2prev[i] = a2;
;                     const float cv = w2[i] * X[i] + w1[i] * q1 + w0[i] * q2 + bb[i];
;                     o[i] = MODE == 0 ? silu_f(cv) * Y[i] : cv * Y[i];
;                 }
;                 if (m == 0 && fr < 2) {
;                     bf16_t* hx = halo + ((size_t)strip * 6 + 2 + fr) * C + c0; bf16_t* hy = halo + ((size_t)strip * 6 + 4 + fr) * C + c0;
;                     u32x4 px, py; px.x = cvt_pk_bf16(X[0], X[1]); px.y = cvt_pk_bf16(X[2], X[3]); px.z = cvt_pk_bf16(X[4 % NV], X[5 % NV]); px.w = cvt_pk_bf16(X[6 % NV], X[7 % NV]);
;                     py.x = cvt_pk_bf16(Y[0], Y[1]); py.y = cvt_pk_bf16(Y[2], Y[3]); py.z = cvt_pk_bf16(Y[4 % NV], Y[5 % NV]); py.w = cvt_pk_bf16(Y[6 % NV], Y[7 % NV]);
;                     if (MODE == 0) { *(u32x4*)hx = px; *(u32x4*)hy = py; } else { u32x2 a; a.x = px.x; a.y = px.y; *(u32x2*)hx = a; u32x2 b; b.x = py.x; b.y = py.y; *(u32x2*)hy = b; }
;                 } else {
;                     if (MODE == 0) { u32x4 w; w.x = cvt_pk_bf16(o[0], o[1]); w.y = cvt_pk_bf16(o[2], o[3]); w.z = cvt_pk_bf16(o[4 % NV], o[5 % NV]); w.w = cvt_pk_bf16(o[6 % NV], o[7 % NV]);
	v_exp_f32_e32 v225, v217
	v_add_f32_e32 v218, 1.0, v218
	v_add_f32_e32 v219, 1.0, v219
	v_add_f32_e32 v220, 1.0, v220
	v_add_f32_e32 v221, 1.0, v221
	v_add_f32_e32 v222, 1.0, v222
	v_add_f32_e32 v223, 1.0, v223
	v_add_f32_e32 v224, 1.0, v224
	v_add_f32_e32 v225, 1.0, v225
	v_rcp_f32_e32 v218, v218
	v_rcp_f32_e32 v219, v219
	v_rcp_f32_e32 v220, v220
	v_rcp_f32_e32 v221, v221
	v_rcp_f32_e32 v222, v222
	v_rcp_f32_e32 v223, v223
	v_rcp_f32_e32 v224, v224
	v_rcp_f32_e32 v225, v225
	v_mul_f32_e32 v156, v156, v202
	v_mul_f32_e32 v157, v157, v202
	v_mul_f32_e32 v158, v158, v202
	v_mul_f32_e32 v159, v159, v202
	v_mul_f32_e32 v148, v148, v202
	v_mul_f32_e32 v149, v149, v202
	v_mul_f32_e32 v150, v150, v202
	v_mul_f32_e32 v151, v151, v202
	v_mul_f32_e32 v210, v210, v218
	v_mul_f32_e32 v211, v211, v219
	v_mul_f32_e32 v212, v212, v220
	v_mul_f32_e32 v213, v213, v221
	v_mul_f32_e32 v214, v214, v222
	v_mul_f32_e32 v215, v215, v223
	v_mul_f32_e32 v216, v216, v224
	v_mul_f32_e32 v217, v217, v225
	v_mul_f32_e32 v156, v210, v156
	v_mul_f32_e32 v157, v211, v157
	v_mul_f32_e32 v158, v212, v158
	v_mul_f32_e32 v159, v213, v159
	v_mul_f32_e32 v148, v214, v148
	v_mul_f32_e32 v149, v215, v149
	v_mul_f32_e32 v150, v216, v150
	v_mul_f32_e32 v151, v217, v151
	v_cvt_pk_bf16_f32 v226, v156, v157
	v_cvt_pk_bf16_f32 v227, v158, v159
	v_cvt_pk_bf16_f32 v228, v148, v149
	v_cvt_pk_bf16_f32 v229, v150, v151
	v_add_u32_e32 v234, 0x0, v230
	s_and_b64 exec, exec, s[8:9]
	global_store_dwordx4 v234, v[226:229], s[96:97] nt
	s_mov_b64 exec, s[24:25]
	v_mul_f32_e32 v124, v124, v183
	v_mul_f32_e32 v125, v125, v183
	v_mul_f32_e32 v126, v126, v183
	v_mul_f32_e32 v127, v127, v183
	v_mul_f32_e32 v120, v120, v183
	v_mul_f32_e32 v121, v121, v183
	v_mul_f32_e32 v122, v122, v183
	v_mul_f32_e32 v123, v123, v183
	v_fma_f32 v210, v124, v136, v174
	v_fma_f32 v211, v125, v137, v175
	v_fma_f32 v212, v126, v138, v176
	v_fma_f32 v213, v127, v139, v177
	v_fma_f32 v214, v120, v140, v178
	v_fma_f32 v215, v121, v141, v179
	v_fma_f32 v216, v122, v142, v180
	v_fma_f32 v217, v123, v143, v181
	v_fmac_f32_dpp v210, v124, v128 row_shr:1 row_mask:0xf bank_mask:0xf
	v_fmac_f32_dpp v211, v125, v129 row_shr:1 row_mask:0xf bank_mask:0xf
	v_fmac_f32_dpp v212, v126, v130 row_shr:1 row_mask:0xf bank_mask:0xf
	v_fmac_f32_dpp v213, v127, v131 row_shr:1 row_mask:0xf bank_mask:0xf
	v_fmac_f32_dpp v214, v120, v132 row_shr:1 row_mask:0xf bank_mask:0xf
	v_fmac_f32_dpp v215, v121, v133 row_shr:1 row_mask:0xf bank_mask:0xf
	v_fmac_f32_dpp v216, v122, v134 row_shr:1 row_mask:0xf bank_mask:0xf
	v_fmac_f32_dpp v217, v123, v135 row_shr:1 row_mask:0xf bank_mask:0xf
	v_fmac_f32_dpp v210, v124, v88 row_shr:2 row_mask:0xf bank_mask:0xf
	v_fmac_f32_dpp v211, v125, v89 row_shr:2 row_mask:0xf bank_mask:0xf
	v_fmac_f32_dpp v212, v126, v90 row_shr:2 row_mask:0xf bank_mask:0xf
	v_fmac_f32_dpp v213, v127, v91 row_shr:2 row_mask:0xf bank_mask:0xf
	v_fmac_f32_dpp v214, v120, v92 row_shr:2 row_mask:0xf bank_mask:0xf
	v_fmac_f32_dpp v215, v121, v93 row_shr:2 row_mask:0xf bank_mask:0xf
	v_fmac_f32_dpp v216, v122, v94 row_shr:2 row_mask:0xf bank_mask:0xf
	v_fmac_f32_dpp v217, v123, v95 row_shr:2 row_mask:0xf bank_mask:0xf
	v_fmac_f32_dpp v210, v152, v128 row_shl:15 row_mask:0xf bank_mask:0xf
	v_fmac_f32_dpp v211, v153, v129 row_shl:15 row_mask:0xf bank_mask:0xf
	v_fmac_f32_dpp v212, v154, v130 row_shl:15 row_mask:0xf bank_mask:0xf
	v_fmac_f32_dpp v213, v155, v131 row_shl:15 row_mask:0xf bank_mask:0xf
	v_fmac_f32_dpp v214, v144, v132 row_shl:15 row_mask:0xf bank_mask:0xf
	v_fmac_f32_dpp v215, v145, v133 row_shl:15 row_mask:0xf bank_mask:0xf
	v_fmac_f32_dpp v216, v146, v134 row_shl:15 row_mask:0xf bank_mask:0xf
	v_fmac_f32_dpp v217, v147, v135 row_shl:15 row_mask:0xf bank_mask:0xf
	v_fmac_f32_dpp v210, v152, v88 row_shl:14 row_mask:0xf bank_mask:0xf
	v_fmac_f32_dpp v211, v153, v89 row_shl:14 row_mask:0xf bank_mask:0xf
	v_fmac_f32_dpp v212, v154, v90 row_shl:14 row_mask:0xf bank_mask:0xf
	v_fmac_f32_dpp v213, v155, v91 row_shl:14 row_mask:0xf bank_mask:0xf
	v_fmac_f32_dpp v214, v144, v92 row_shl:14 row_mask:0xf bank_mask:0xf
	v_fmac_f32_dpp v215, v145, v93 row_shl:14 row_mask:0xf bank_mask:0xf
	v_fmac_f32_dpp v216, v146, v94 row_shl:14 row_mask:0xf bank_mask:0xf
	v_fmac_f32_dpp v217, v147, v95 row_shl:14 row_mask:0xf bank_mask:0xf
	v_exp_f32_e32 v218, v210
	v_exp_f32_e32 v219, v211
	v_exp_f32_e32 v220, v212
	v_exp_f32_e32 v221, v213
	v_exp_f32_e32 v222, v214
	v_exp_f32_e32 v223, v215
	v_exp_f32_e32 v224, v216
	v_exp_f32_e32 v225, v217
	v_add_f32_e32 v218, 1.0, v218
	v_add_f32_e32 v219, 1.0, v219
	v_add_f32_e32 v220, 1.0, v220
	v_add_f32_e32 v221, 1.0, v221
	v_add_f32_e32 v222, 1.0, v222
	v_add_f32_e32 v223, 1.0, v223
	v_add_f32_e32 v224, 1.0, v224
	v_add_f32_e32 v225, 1.0, v225
	v_rcp_f32_e32 v218, v218
	v_rcp_f32_e32 v219, v219
	v_rcp_f32_e32 v220, v220
	v_rcp_f32_e32 v221, v221
	v_rcp_f32_e32 v222, v222
	v_rcp_f32_e32 v223, v223
	v_rcp_f32_e32 v224, v224
	v_rcp_f32_e32 v225, v225
	v_mul_f32_e32 v116, v116, v203
	v_mul_f32_e32 v117, v117, v203
	v_mul_f32_e32 v118, v118, v203
	v_mul_f32_e32 v119, v119, v203
	v_mul_f32_e32 v112, v112, v203
	v_mul_f32_e32 v113, v113, v203
	v_mul_f32_e32 v114, v114, v203
	v_mul_f32_e32 v115, v115, v203
	v_mul_f32_e32 v210, v210, v218
	v_mul_f32_e32 v211, v211, v219
	v_mul_f32_e32 v212, v212, v220
	v_mul_f32_e32 v213, v213, v221
	v_mul_f32_e32 v214, v214, v222
	v_mul_f32_e32 v215, v215, v223
	v_mul_f32_e32 v216, v216, v224
	v_mul_f32_e32 v217, v217, v225
	v_mul_f32_e32 v116, v210, v116
	v_mul_f32_e32 v117, v211, v117
	v_mul_f32_e32 v118, v212, v118
	v_mul_f32_e32 v119, v213, v119
	v_mul_f32_e32 v112, v214, v112
;     __device__ __forceinline__ void operator()(const Acc& acc, const Unit& u, int wr, int wc, int fr, int fq, LAS unsigned char* lds, f32x4 epar) const {
;     ...
;             for (int m = 0; m < 4; ++m) {
;                 const int r = u.pm * BM + ai * HALF + wr * 64 + m * 16 + fr;
;                 const float rs = __builtin_amdgcn_rsqf(sq[ai][m] * (1.0f / DM) + RMS_EPS);
;                 float X[NV], Y[NV], o[NV];
;                 if (MODE == 0) {
; #pragma unroll
;                     for (int n = 0; n < 2; ++n)
; #pragma unroll
;                         for (int j = 0; j < 4; ++j) { X[n * 4 + j] = acc[ai][0][m][n][j] * rs; Y[n * 4 + j] = acc[ai][1][m][n][j] * rs; }
;                 } else {
; #pragma unroll
;                     for (int j = 0; j < 4; ++j) { X[j] = (acc[ai][0][m][1][j] * rs) * (acc[ai][1][m][0][j] * rs); Y[j] = acc[ai][0][m][0][j] * rs; }
;                 }
; #pragma unroll
;                 for (int i = 0; i < NV; ++i) {
;                     const float a1 = dpp_rot<0x121>(X[i]), a2 = dpp_rot<0x122>(X[i]);
;                     const float q1 = fr >= 1 ? a1 : p1prev[i], q2 = fr >= 2 ? a2 : p2prev[i];
;                     p1prev[i] = a1; p2prev[i] = a2;
;                     const float cv = w2[i] * X[i] + w1[i] * q1 + w0[i] * q2 + bb[i];
;                     o[i] = MODE == 0 ? silu_f(cv) * Y[i] : cv * Y[i];
;                 }
;                 if (m == 0 && fr < 2) {
;                     bf16_t* hx = halo + ((size_t)strip * 6 + 2 + fr) * C + c0; bf16_t* hy = halo + ((size_t)strip * 6 + 4 + fr) * C + c0;
;                     u32x4 px, py; px.x = cvt_pk_bf16(X[0], X[1]); px.y = cvt_pk_bf16(X[2], X[3]); px.z = cvt_pk_bf16(X[4 % NV], X[5 % NV]); px.w = cvt_pk_bf16(X[6 % NV], X[7 % NV]);
;                     py.x = cvt_pk_bf16(Y[0], Y[1]); py.y = cvt_pk_bf16(Y[2], Y[3]); py.z = cvt_pk_bf16(Y[4 % NV], Y[5 % NV]); py.w = cvt_pk_bf16(Y[6 % NV], Y[7 % NV]);
;                     if (MODE == 0) { *(u32x4*)hx = px; *(u32x4*)hy = py; } else { u32x2 a; a.x = px.x; a.y = px.y; *(u32x2*)hx = a; u32x2 b; b.x = py.x; b.y = py.y; *(u32x2*)hy = b; }
;                 } else {
;                     if (MODE == 0) { u32x4 w; w.x = cvt_pk_bf16(o[0], o[1]); w.y = cvt_pk_bf16(o[2], o[3]); w.z = cvt_pk_bf16(o[4 % NV], o[5 % NV]); w.w = cvt_pk_bf16(o[6 % NV], o[7 % NV]);
	v_mul_f32_e32 v113, v215, v113
	v_mul_f32_e32 v114, v216, v114
	v_mul_f32_e32 v115, v217, v115
	v_cvt_pk_bf16_f32 v226, v116, v117
	v_cvt_pk_bf16_f32 v227, v118, v119
	v_cvt_pk_bf16_f32 v228, v112, v113
	v_cvt_pk_bf16_f32 v229, v114, v115
	v_add_u32_e32 v234, 0x16000, v230
	global_store_dwordx4 v234, v[226:229], s[96:97] nt
	v_mul_f32_e32 v108, v108, v184
	v_mul_f32_e32 v109, v109, v184
	v_mul_f32_e32 v110, v110, v184
	v_mul_f32_e32 v111, v111, v184
	v_mul_f32_e32 v104, v104, v184
	v_mul_f32_e32 v105, v105, v184
	v_mul_f32_e32 v106, v106, v184
	v_mul_f32_e32 v107, v107, v184
	v_fma_f32 v210, v108, v136, v174
	v_fma_f32 v211, v109, v137, v175
	v_fma_f32 v212, v110, v138, v176
	v_fma_f32 v213, v111, v139, v177
	v_fma_f32 v214, v104, v140, v178
	v_fma_f32 v215, v105, v141, v179
	v_fma_f32 v216, v106, v142, v180
	v_fma_f32 v217, v107, v143, v181
	v_fmac_f32_dpp v210, v108, v128 row_shr:1 row_mask:0xf bank_mask:0xf
	v_fmac_f32_dpp v211, v109, v129 row_shr:1 row_mask:0xf bank_mask:0xf
	v_fmac_f32_dpp v212, v110, v130 row_shr:1 row_mask:0xf bank_mask:0xf
	v_fmac_f32_dpp v213, v111, v131 row_shr:1 row_mask:0xf bank_mask:0xf
	v_fmac_f32_dpp v214, v104, v132 row_shr:1 row_mask:0xf bank_mask:0xf
	v_fmac_f32_dpp v215, v105, v133 row_shr:1 row_mask:0xf bank_mask:0xf
	v_fmac_f32_dpp v216, v106, v134 row_shr:1 row_mask:0xf bank_mask:0xf
	v_fmac_f32_dpp v217, v107, v135 row_shr:1 row_mask:0xf bank_mask:0xf
	v_fmac_f32_dpp v210, v108, v88 row_shr:2 row_mask:0xf bank_mask:0xf
	v_fmac_f32_dpp v211, v109, v89 row_shr:2 row_mask:0xf bank_mask:0xf
	v_fmac_f32_dpp v212, v110, v90 row_shr:2 row_mask:0xf bank_mask:0xf
	v_fmac_f32_dpp v213, v111, v91 row_shr:2 row_mask:0xf bank_mask:0xf
	v_fmac_f32_dpp v214, v104, v92 row_shr:2 row_mask:0xf bank_mask:0xf
	v_fmac_f32_dpp v215, v105, v93 row_shr:2 row_mask:0xf bank_mask:0xf
	v_fmac_f32_dpp v216, v106, v94 row_shr:2 row_mask:0xf bank_mask:0xf
	v_fmac_f32_dpp v217, v107, v95 row_shr:2 row_mask:0xf bank_mask:0xf
	v_fmac_f32_dpp v210, v124, v128 row_shl:15 row_mask:0xf bank_mask:0xf
	v_fmac_f32_dpp v211, v125, v129 row_shl:15 row_mask:0xf bank_mask:0xf
	v_fmac_f32_dpp v212, v126, v130 row_shl:15 row_mask:0xf bank_mask:0xf
	v_fmac_f32_dpp v213, v127, v131 row_shl:15 row_mask:0xf bank_mask:0xf
	v_fmac_f32_dpp v214, v120, v132 row_shl:15 row_mask:0xf bank_mask:0xf
	v_fmac_f32_dpp v215, v121, v133 row_shl:15 row_mask:0xf bank_mask:0xf
	v_fmac_f32_dpp v216, v122, v134 row_shl:15 row_mask:0xf bank_mask:0xf
	v_fmac_f32_dpp v217, v123, v135 row_shl:15 row_mask:0xf bank_mask:0xf
	v_fmac_f32_dpp v210, v124, v88 row_shl:14 row_mask:0xf bank_mask:0xf
	v_fmac_f32_dpp v211, v125, v89 row_shl:14 row_mask:0xf bank_mask:0xf
	v_fmac_f32_dpp v212, v126, v90 row_shl:14 row_mask:0xf bank_mask:0xf
	v_fmac_f32_dpp v213, v127, v91 row_shl:14 row_mask:0xf bank_mask:0xf
	v_fmac_f32_dpp v214, v120, v92 row_shl:14 row_mask:0xf bank_mask:0xf
	v_fmac_f32_dpp v215, v121, v93 row_shl:14 row_mask:0xf bank_mask:0xf
	v_fmac_f32_dpp v216, v122, v94 row_shl:14 row_mask:0xf bank_mask:0xf
	v_fmac_f32_dpp v217, v123, v95 row_shl:14 row_mask:0xf bank_mask:0xf
	v_exp_f32_e32 v218, v210
	v_exp_f32_e32 v219, v211
	v_exp_f32_e32 v220, v212
	v_exp_f32_e32 v221, v213
	v_exp_f32_e32 v222, v214
	v_exp_f32_e32 v223, v215
	v_exp_f32_e32 v224, v216
	v_exp_f32_e32 v225, v217
	v_add_f32_e32 v218, 1.0, v218
	v_add_f32_e32 v219, 1.0, v219
	v_add_f32_e32 v220, 1.0, v220
	v_add_f32_e32 v221, 1.0, v221
	v_add_f32_e32 v222, 1.0, v222
	v_add_f32_e32 v223, 1.0, v223
	v_add_f32_e32 v224, 1.0, v224
	v_add_f32_e32 v225, 1.0, v225
	v_rcp_f32_e32 v218, v218
	v_rcp_f32_e32 v219, v219
	v_rcp_f32_e32 v220, v220
	v_rcp_f32_e32 v221, v221
	v_rcp_f32_e32 v222, v222
	v_rcp_f32_e32 v223, v223
	v_rcp_f32_e32 v224, v224
	v_rcp_f32_e32 v225, v225
	v_mul_f32_e32 v100, v100, v204
	v_mul_f32_e32 v101, v101, v204
	v_mul_f32_e32 v102, v102, v204
	v_mul_f32_e32 v103, v103, v204
	v_mul_f32_e32 v96, v96, v204
	v_mul_f32_e32 v97, v97, v204
	v_mul_f32_e32 v98, v98, v204
	v_mul_f32_e32 v99, v99, v204
	v_mul_f32_e32 v210, v210, v218
	v_mul_f32_e32 v211, v211, v219
	v_mul_f32_e32 v212, v212, v220
	v_mul_f32_e32 v213, v213, v221
	v_mul_f32_e32 v214, v214, v222
	v_mul_f32_e32 v215, v215, v223
	v_mul_f32_e32 v216, v216, v224
	v_mul_f32_e32 v217, v217, v225
	v_mul_f32_e32 v100, v210, v100
	v_mul_f32_e32 v101, v211, v101
	v_mul_f32_e32 v102, v212, v102
	v_mul_f32_e32 v103, v213, v103
	v_mul_f32_e32 v96, v214, v96
	v_mul_f32_e32 v97, v215, v97
	v_mul_f32_e32 v98, v216, v98
	v_mul_f32_e32 v99, v217, v99
	v_cvt_pk_bf16_f32 v226, v100, v101
	v_cvt_pk_bf16_f32 v227, v102, v103
	v_cvt_pk_bf16_f32 v228, v96, v97
	v_cvt_pk_bf16_f32 v229, v98, v99
	v_add_u32_e32 v234, 0x2c000, v230
	global_store_dwordx4 v234, v[226:229], s[96:97] nt
	v_mul_f32_e32 v84, v84, v185
	v_mul_f32_e32 v85, v85, v185
	v_mul_f32_e32 v86, v86, v185
	v_mul_f32_e32 v87, v87, v185
	v_mul_f32_e32 v80, v80, v185
	v_mul_f32_e32 v81, v81, v185
	v_mul_f32_e32 v82, v82, v185
	v_mul_f32_e32 v83, v83, v185
	v_fma_f32 v210, v84, v136, v174
	v_fma_f32 v211, v85, v137, v175
	v_fma_f32 v212, v86, v138, v176
	v_fma_f32 v213, v87, v139, v177
	v_fma_f32 v214, v80, v140, v178
	v_fma_f32 v215, v81, v141, v179
	v_fma_f32 v216, v82, v142, v180
	v_fma_f32 v217, v83, v143, v181
	v_cvt_pk_bf16_f32 v236, v84, v85
	v_cvt_pk_bf16_f32 v237, v86, v87
	v_cvt_pk_bf16_f32 v238, v80, v81
	v_cvt_pk_bf16_f32 v239, v82, v83
	v_add_u32_e32 v235, 0xfffecc00, v233
	s_and_b64 exec, exec, s[10:11]
	global_store_dwordx4 v235, v[236:239], s[42:43]
	s_mov_b64 exec, s[24:25]
	v_fmac_f32_dpp v210, v84, v128 row_shr:1 row_mask:0xf bank_mask:0xf
	v_fmac_f32_dpp v211, v85, v129 row_shr:1 row_mask:0xf bank_mask:0xf
;     __device__ __forceinline__ void operator()(const Acc& acc, const Unit& u, int wr, int wc, int fr, int fq, LAS unsigned char* lds, f32x4 epar) const {
;     ...
;             for (int m = 0; m < 4; ++m) {
;                 const int r = u.pm * BM + ai * HALF + wr * 64 + m * 16 + fr;
;                 const float rs = __builtin_amdgcn_rsqf(sq[ai][m] * (1.0f / DM) + RMS_EPS);
;                 float X[NV], Y[NV], o[NV];
;                 if (MODE == 0) {
; #pragma unroll
;                     for (int n = 0; n < 2; ++n)
; #pragma unroll
;                         for (int j = 0; j < 4; ++j) { X[n * 4 + j] = acc[ai][0][m][n][j] * rs; Y[n * 4 + j] = acc[ai][1][m][n][j] * rs; }
;                 } else {
; #pragma unroll
;                     for (int j = 0; j < 4; ++j) { X[j] = (acc[ai][0][m][1][j] * rs) * (acc[ai][1][m][0][j] * rs); Y[j] = acc[ai][0][m][0][j] * rs; }
;                 }
; #pragma unroll
;                 for (int i = 0; i < NV; ++i) {
;                     const float a1 = dpp_rot<0x121>(X[i]), a2 = dpp_rot<0x122>(X[i]);
;                     const float q1 = fr >= 1 ? a1 : p1prev[i], q2 = fr >= 2 ? a2 : p2prev[i];
;                     p1prev[i] = a1; p2prev[i] = a2;
;                     const float cv = w2[i] * X[i] + w1[i] * q1 + w0[i] * q2 + bb[i];
;                     o[i] = MODE == 0 ? silu_f(cv) * Y[i] : cv * Y[i];
;                 }
;                 if (m == 0 && fr < 2) {
;                     bf16_t* hx = halo + ((size_t)strip * 6 + 2 + fr) * C + c0; bf16_t* hy = halo + ((size_t)strip * 6 + 4 + fr) * C + c0;
;                     u32x4 px, py; px.x = cvt_pk_bf16(X[0], X[1]); px.y = cvt_pk_bf16(X[2], X[3]); px.z = cvt_pk_bf16(X[4 % NV], X[5 % NV]); px.w = cvt_pk_bf16(X[6 % NV], X[7 % NV]);
;                     py.x = cvt_pk_bf16(Y[0], Y[1]); py.y = cvt_pk_bf16(Y[2], Y[3]); py.z = cvt_pk_bf16(Y[4 % NV], Y[5 % NV]); py.w = cvt_pk_bf16(Y[6 % NV], Y[7 % NV]);
;                     if (MODE == 0) { *(u32x4*)hx = px; *(u32x4*)hy = py; } else { u32x2 a; a.x = px.x; a.y = px.y; *(u32x2*)hx = a; u32x2 b; b.x = py.x; b.y = py.y; *(u32x2*)hy = b; }
;                 } else {
;                     if (MODE == 0) { u32x4 w; w.x = cvt_pk_bf16(o[0], o[1]); w.y = cvt_pk_bf16(o[2], o[3]); w.z = cvt_pk_bf16(o[4 % NV], o[5 % NV]); w.w = cvt_pk_bf16(o[6 % NV], o[7 % NV]);
	v_fmac_f32_dpp v212, v86, v130 row_shr:1 row_mask:0xf bank_mask:0xf
	v_fmac_f32_dpp v213, v87, v131 row_shr:1 row_mask:0xf bank_mask:0xf
	v_fmac_f32_dpp v214, v80, v132 row_shr:1 row_mask:0xf bank_mask:0xf
	v_fmac_f32_dpp v215, v81, v133 row_shr:1 row_mask:0xf bank_mask:0xf
	v_fmac_f32_dpp v216, v82, v134 row_shr:1 row_mask:0xf bank_mask:0xf
	v_fmac_f32_dpp v217, v83, v135 row_shr:1 row_mask:0xf bank_mask:0xf
	v_fmac_f32_dpp v210, v84, v88 row_shr:2 row_mask:0xf bank_mask:0xf
	v_fmac_f32_dpp v211, v85, v89 row_shr:2 row_mask:0xf bank_mask:0xf
	v_fmac_f32_dpp v212, v86, v90 row_shr:2 row_mask:0xf bank_mask:0xf
	v_fmac_f32_dpp v213, v87, v91 row_shr:2 row_mask:0xf bank_mask:0xf
	v_fmac_f32_dpp v214, v80, v92 row_shr:2 row_mask:0xf bank_mask:0xf
	v_fmac_f32_dpp v215, v81, v93 row_shr:2 row_mask:0xf bank_mask:0xf
	v_fmac_f32_dpp v216, v82, v94 row_shr:2 row_mask:0xf bank_mask:0xf
	v_fmac_f32_dpp v217, v83, v95 row_shr:2 row_mask:0xf bank_mask:0xf
	v_fmac_f32_dpp v210, v108, v128 row_shl:15 row_mask:0xf bank_mask:0xf
	v_fmac_f32_dpp v211, v109, v129 row_shl:15 row_mask:0xf bank_mask:0xf
	v_fmac_f32_dpp v212, v110, v130 row_shl:15 row_mask:0xf bank_mask:0xf
	v_fmac_f32_dpp v213, v111, v131 row_shl:15 row_mask:0xf bank_mask:0xf
	v_fmac_f32_dpp v214, v104, v132 row_shl:15 row_mask:0xf bank_mask:0xf
	v_fmac_f32_dpp v215, v105, v133 row_shl:15 row_mask:0xf bank_mask:0xf
	v_fmac_f32_dpp v216, v106, v134 row_shl:15 row_mask:0xf bank_mask:0xf
	v_fmac_f32_dpp v217, v107, v135 row_shl:15 row_mask:0xf bank_mask:0xf
	v_fmac_f32_dpp v210, v108, v88 row_shl:14 row_mask:0xf bank_mask:0xf
	v_fmac_f32_dpp v211, v109, v89 row_shl:14 row_mask:0xf bank_mask:0xf
	v_fmac_f32_dpp v212, v110, v90 row_shl:14 row_mask:0xf bank_mask:0xf
	v_fmac_f32_dpp v213, v111, v91 row_shl:14 row_mask:0xf bank_mask:0xf
	v_fmac_f32_dpp v214, v104, v92 row_shl:14 row_mask:0xf bank_mask:0xf
	v_fmac_f32_dpp v215, v105, v93 row_shl:14 row_mask:0xf bank_mask:0xf
	v_fmac_f32_dpp v216, v106, v94 row_shl:14 row_mask:0xf bank_mask:0xf
	v_fmac_f32_dpp v217, v107, v95 row_shl:14 row_mask:0xf bank_mask:0xf
	v_exp_f32_e32 v218, v210
	v_exp_f32_e32 v219, v211
	v_exp_f32_e32 v220, v212
	v_exp_f32_e32 v221, v213
	v_exp_f32_e32 v222, v214
	v_exp_f32_e32 v223, v215
	v_exp_f32_e32 v224, v216
	v_exp_f32_e32 v225, v217
	v_add_f32_e32 v218, 1.0, v218
	v_add_f32_e32 v219, 1.0, v219
	v_add_f32_e32 v220, 1.0, v220
	v_add_f32_e32 v221, 1.0, v221
	v_add_f32_e32 v222, 1.0, v222
	v_add_f32_e32 v223, 1.0, v223
	v_add_f32_e32 v224, 1.0, v224
	v_add_f32_e32 v225, 1.0, v225
	v_rcp_f32_e32 v218, v218
	v_rcp_f32_e32 v219, v219
	v_rcp_f32_e32 v220, v220
	v_rcp_f32_e32 v221, v221
	v_rcp_f32_e32 v222, v222
	v_rcp_f32_e32 v223, v223
	v_rcp_f32_e32 v224, v224
	v_rcp_f32_e32 v225, v225
	v_mul_f32_e32 v68, v68, v205
	v_mul_f32_e32 v69, v69, v205
	v_mul_f32_e32 v70, v70, v205
	v_mul_f32_e32 v71, v71, v205
	v_mul_f32_e32 v64, v64, v205
	v_mul_f32_e32 v65, v65, v205
	v_mul_f32_e32 v66, v66, v205
	v_mul_f32_e32 v67, v67, v205
	v_mul_f32_e32 v210, v210, v218
	v_mul_f32_e32 v211, v211, v219
	v_mul_f32_e32 v212, v212, v220
	v_mul_f32_e32 v213, v213, v221
	v_mul_f32_e32 v214, v214, v222
	v_mul_f32_e32 v215, v215, v223
	v_mul_f32_e32 v216, v216, v224
	v_mul_f32_e32 v217, v217, v225
	v_mul_f32_e32 v68, v210, v68
	v_mul_f32_e32 v69, v211, v69
	v_mul_f32_e32 v70, v212, v70
	v_mul_f32_e32 v71, v213, v71
	v_mul_f32_e32 v64, v214, v64
	v_mul_f32_e32 v65, v215, v65
	v_mul_f32_e32 v66, v216, v66
	v_mul_f32_e32 v67, v217, v67
	v_cvt_pk_bf16_f32 v226, v68, v69
	v_cvt_pk_bf16_f32 v227, v70, v71
	v_cvt_pk_bf16_f32 v228, v64, v65
	v_cvt_pk_bf16_f32 v229, v66, v67
	v_add_u32_e32 v234, 0x42000, v230
	global_store_dwordx4 v234, v[226:229], s[96:97] nt
	v_mul_f32_e32 v60, v60, v76
	v_mul_f32_e32 v61, v61, v76
	v_mul_f32_e32 v62, v62, v76
	v_mul_f32_e32 v63, v63, v76
	v_mul_f32_e32 v52, v52, v76
	v_mul_f32_e32 v53, v53, v76
	v_mul_f32_e32 v54, v54, v76
	v_mul_f32_e32 v55, v55, v76
	v_fma_f32 v210, v60, v136, v174
	v_fma_f32 v211, v61, v137, v175
	v_fma_f32 v212, v62, v138, v176
	v_fma_f32 v213, v63, v139, v177
	v_fma_f32 v214, v52, v140, v178
	v_fma_f32 v215, v53, v141, v179
	v_fma_f32 v216, v54, v142, v180
	v_fma_f32 v217, v55, v143, v181
	v_mul_f32_e32 v218, v56, v76
	v_mul_f32_e32 v219, v57, v76
	v_mul_f32_e32 v220, v58, v76
	v_mul_f32_e32 v221, v59, v76
	v_mul_f32_e32 v222, v48, v76
	v_mul_f32_e32 v223, v49, v76
	v_mul_f32_e32 v224, v50, v76
	v_mul_f32_e32 v225, v51, v76
	v_cvt_pk_bf16_f32 v236, v60, v61
	v_cvt_pk_bf16_f32 v237, v62, v63
	v_cvt_pk_bf16_f32 v238, v52, v53
	v_cvt_pk_bf16_f32 v239, v54, v55
	v_cvt_pk_bf16_f32 v240, v218, v219
	v_cvt_pk_bf16_f32 v241, v220, v221
	v_cvt_pk_bf16_f32 v242, v222, v223
	v_cvt_pk_bf16_f32 v243, v224, v225
	v_add_u32_e32 v234, 0x13400, v233
	v_add_u32_e32 v235, 0x16000, v233
	s_andn2_b64 exec, exec, s[8:9]
	global_store_dwordx4 v234, v[236:239], s[42:43]
	global_store_dwordx4 v235, v[240:243], s[42:43]
	s_mov_b64 exec, s[24:25]
	v_fmac_f32_dpp v210, v60, v128 row_shr:1 row_mask:0xf bank_mask:0xf
	v_fmac_f32_dpp v211, v61, v129 row_shr:1 row_mask:0xf bank_mask:0xf
	v_fmac_f32_dpp v212, v62, v130 row_shr:1 row_mask:0xf bank_mask:0xf
	v_fmac_f32_dpp v213, v63, v131 row_shr:1 row_mask:0xf bank_mask:0xf
	v_fmac_f32_dpp v214, v52, v132 row_shr:1 row_mask:0xf bank_mask:0xf
	v_fmac_f32_dpp v215, v53, v133 row_shr:1 row_mask:0xf bank_mask:0xf
	v_fmac_f32_dpp v216, v54, v134 row_shr:1 row_mask:0xf bank_mask:0xf
	v_fmac_f32_dpp v217, v55, v135 row_shr:1 row_mask:0xf bank_mask:0xf
	v_fmac_f32_dpp v210, v60, v88 row_shr:2 row_mask:0xf bank_mask:0xf
	v_fmac_f32_dpp v211, v61, v89 row_shr:2 row_mask:0xf bank_mask:0xf
;     __device__ __forceinline__ void operator()(const Acc& acc, const Unit& u, int wr, int wc, int fr, int fq, LAS unsigned char* lds, f32x4 epar) const {
;     ...
;             for (int m = 0; m < 4; ++m) {
;                 const int r = u.pm * BM + ai * HALF + wr * 64 + m * 16 + fr;
;                 const float rs = __builtin_amdgcn_rsqf(sq[ai][m] * (1.0f / DM) + RMS_EPS);
;                 float X[NV], Y[NV], o[NV];
;                 if (MODE == 0) {
; #pragma unroll
;                     for (int n = 0; n < 2; ++n)
; #pragma unroll
;                         for (int j = 0; j < 4; ++j) { X[n * 4 + j] = acc[ai][0][m][n][j] * rs; Y[n * 4 + j] = acc[ai][1][m][n][j] * rs; }
;                 } else {
; #pragma unroll
;                     for (int j = 0; j < 4; ++j) { X[j] = (acc[ai][0][m][1][j] * rs) * (acc[ai][1][m][0][j] * rs); Y[j] = acc[ai][0][m][0][j] * rs; }
;                 }
; #pragma unroll
;                 for (int i = 0; i < NV; ++i) {
;                     const float a1 = dpp_rot<0x121>(X[i]), a2 = dpp_rot<0x122>(X[i]);
;                     const float q1 = fr >= 1 ? a1 : p1prev[i], q2 = fr >= 2 ? a2 : p2prev[i];
;                     p1prev[i] = a1; p2prev[i] = a2;
;                     const float cv = w2[i] * X[i] + w1[i] * q1 + w0[i] * q2 + bb[i];
;                     o[i] = MODE == 0 ? silu_f(cv) * Y[i] : cv * Y[i];
;                 }
;                 if (m == 0 && fr < 2) {
;                     bf16_t* hx = halo + ((size_t)strip * 6 + 2 + fr) * C + c0; bf16_t* hy = halo + ((size_t)strip * 6 + 4 + fr) * C + c0;
;                     u32x4 px, py; px.x = cvt_pk_bf16(X[0], X[1]); px.y = cvt_pk_bf16(X[2], X[3]); px.z = cvt_pk_bf16(X[4 % NV], X[5 % NV]); px.w = cvt_pk_bf16(X[6 % NV], X[7 % NV]);
;                     py.x = cvt_pk_bf16(Y[0], Y[1]); py.y = cvt_pk_bf16(Y[2], Y[3]); py.z = cvt_pk_bf16(Y[4 % NV], Y[5 % NV]); py.w = cvt_pk_bf16(Y[6 % NV], Y[7 % NV]);
;                     if (MODE == 0) { *(u32x4*)hx = px; *(u32x4*)hy = py; } else { u32x2 a; a.x = px.x; a.y = px.y; *(u32x2*)hx = a; u32x2 b; b.x = py.x; b.y = py.y; *(u32x2*)hy = b; }
;                 } else {
;                     if (MODE == 0) { u32x4 w; w.x = cvt_pk_bf16(o[0], o[1]); w.y = cvt_pk_bf16(o[2], o[3]); w.z = cvt_pk_bf16(o[4 % NV], o[5 % NV]); w.w = cvt_pk_bf16(o[6 % NV], o[7 % NV]);
	v_fmac_f32_dpp v212, v62, v90 row_shr:2 row_mask:0xf bank_mask:0xf
	v_fmac_f32_dpp v213, v63, v91 row_shr:2 row_mask:0xf bank_mask:0xf
	v_fmac_f32_dpp v214, v52, v92 row_shr:2 row_mask:0xf bank_mask:0xf
	v_fmac_f32_dpp v215, v53, v93 row_shr:2 row_mask:0xf bank_mask:0xf
	v_fmac_f32_dpp v216, v54, v94 row_shr:2 row_mask:0xf bank_mask:0xf
	v_fmac_f32_dpp v217, v55, v95 row_shr:2 row_mask:0xf bank_mask:0xf
	v_exp_f32_e32 v218, v210
	v_exp_f32_e32 v219, v211
	v_exp_f32_e32 v220, v212
	v_exp_f32_e32 v221, v213
	v_exp_f32_e32 v222, v214
	v_exp_f32_e32 v223, v215
	v_exp_f32_e32 v224, v216
	v_exp_f32_e32 v225, v217
	v_add_f32_e32 v218, 1.0, v218
	v_add_f32_e32 v219, 1.0, v219
	v_add_f32_e32 v220, 1.0, v220
	v_add_f32_e32 v221, 1.0, v221
	v_add_f32_e32 v222, 1.0, v222
	v_add_f32_e32 v223, 1.0, v223
	v_add_f32_e32 v224, 1.0, v224
	v_add_f32_e32 v225, 1.0, v225
	v_rcp_f32_e32 v218, v218
	v_rcp_f32_e32 v219, v219
	v_rcp_f32_e32 v220, v220
	v_rcp_f32_e32 v221, v221
	v_rcp_f32_e32 v222, v222
	v_rcp_f32_e32 v223, v223
	v_rcp_f32_e32 v224, v224
	v_rcp_f32_e32 v225, v225
	v_mul_f32_e32 v56, v56, v206
	v_mul_f32_e32 v57, v57, v206
	v_mul_f32_e32 v58, v58, v206
	v_mul_f32_e32 v59, v59, v206
	v_mul_f32_e32 v48, v48, v206
	v_mul_f32_e32 v49, v49, v206
	v_mul_f32_e32 v50, v50, v206
	v_mul_f32_e32 v51, v51, v206
	v_mul_f32_e32 v210, v210, v218
	v_mul_f32_e32 v211, v211, v219
	v_mul_f32_e32 v212, v212, v220
	v_mul_f32_e32 v213, v213, v221
	v_mul_f32_e32 v214, v214, v222
	v_mul_f32_e32 v215, v215, v223
	v_mul_f32_e32 v216, v216, v224
	v_mul_f32_e32 v217, v217, v225
	v_mul_f32_e32 v56, v210, v56
	v_mul_f32_e32 v57, v211, v57
	v_mul_f32_e32 v58, v212, v58
	v_mul_f32_e32 v59, v213, v59
	v_mul_f32_e32 v48, v214, v48
	v_mul_f32_e32 v49, v215, v49
	v_mul_f32_e32 v50, v216, v50
	v_mul_f32_e32 v51, v217, v51
	v_cvt_pk_bf16_f32 v226, v56, v57
	v_cvt_pk_bf16_f32 v227, v58, v59
	v_cvt_pk_bf16_f32 v228, v48, v49
	v_cvt_pk_bf16_f32 v229, v50, v51
	v_add_u32_e32 v234, 0xb0000, v230
	s_and_b64 exec, exec, s[8:9]
	global_store_dwordx4 v234, v[226:229], s[96:97] nt
	s_mov_b64 exec, s[24:25]
	v_mul_f32_e32 v44, v44, v77
	v_mul_f32_e32 v45, v45, v77
	v_mul_f32_e32 v46, v46, v77
	v_mul_f32_e32 v47, v47, v77
	v_mul_f32_e32 v40, v40, v77
	v_mul_f32_e32 v41, v41, v77
	v_mul_f32_e32 v42, v42, v77
	v_mul_f32_e32 v43, v43, v77
	v_fma_f32 v210, v44, v136, v174
	v_fma_f32 v211, v45, v137, v175
	v_fma_f32 v212, v46, v138, v176
	v_fma_f32 v213, v47, v139, v177
	v_fma_f32 v214, v40, v140, v178
	v_fma_f32 v215, v41, v141, v179
	v_fma_f32 v216, v42, v142, v180
	v_fma_f32 v217, v43, v143, v181
	v_fmac_f32_dpp v210, v44, v128 row_shr:1 row_mask:0xf bank_mask:0xf
	v_fmac_f32_dpp v211, v45, v129 row_shr:1 row_mask:0xf bank_mask:0xf
	v_fmac_f32_dpp v212, v46, v130 row_shr:1 row_mask:0xf bank_mask:0xf
	v_fmac_f32_dpp v213, v47, v131 row_shr:1 row_mask:0xf bank_mask:0xf
	v_fmac_f32_dpp v214, v40, v132 row_shr:1 row_mask:0xf bank_mask:0xf
	v_fmac_f32_dpp v215, v41, v133 row_shr:1 row_mask:0xf bank_mask:0xf
	v_fmac_f32_dpp v216, v42, v134 row_shr:1 row_mask:0xf bank_mask:0xf
	v_fmac_f32_dpp v217, v43, v135 row_shr:1 row_mask:0xf bank_mask:0xf
	v_fmac_f32_dpp v210, v44, v88 row_shr:2 row_mask:0xf bank_mask:0xf
	v_fmac_f32_dpp v211, v45, v89 row_shr:2 row_mask:0xf bank_mask:0xf
	v_fmac_f32_dpp v212, v46, v90 row_shr:2 row_mask:0xf bank_mask:0xf
	v_fmac_f32_dpp v213, v47, v91 row_shr:2 row_mask:0xf bank_mask:0xf
	v_fmac_f32_dpp v214, v40, v92 row_shr:2 row_mask:0xf bank_mask:0xf
	v_fmac_f32_dpp v215, v41, v93 row_shr:2 row_mask:0xf bank_mask:0xf
	v_fmac_f32_dpp v216, v42, v94 row_shr:2 row_mask:0xf bank_mask:0xf
	v_fmac_f32_dpp v217, v43, v95 row_shr:2 row_mask:0xf bank_mask:0xf
	v_fmac_f32_dpp v210, v60, v128 row_shl:15 row_mask:0xf bank_mask:0xf
	v_fmac_f32_dpp v211, v61, v129 row_shl:15 row_mask:0xf bank_mask:0xf
	v_fmac_f32_dpp v212, v62, v130 row_shl:15 row_mask:0xf bank_mask:0xf
	v_fmac_f32_dpp v213, v63, v131 row_shl:15 row_mask:0xf bank_mask:0xf
	v_fmac_f32_dpp v214, v52, v132 row_shl:15 row_mask:0xf bank_mask:0xf
	v_fmac_f32_dpp v215, v53, v133 row_shl:15 row_mask:0xf bank_mask:0xf
	v_fmac_f32_dpp v216, v54, v134 row_shl:15 row_mask:0xf bank_mask:0xf
	v_fmac_f32_dpp v217, v55, v135 row_shl:15 row_mask:0xf bank_mask:0xf
	v_fmac_f32_dpp v210, v60, v88 row_shl:14 row_mask:0xf bank_mask:0xf
	v_fmac_f32_dpp v211, v61, v89 row_shl:14 row_mask:0xf bank_mask:0xf
	v_fmac_f32_dpp v212, v62, v90 row_shl:14 row_mask:0xf bank_mask:0xf
	v_fmac_f32_dpp v213, v63, v91 row_shl:14 row_mask:0xf bank_mask:0xf
	v_fmac_f32_dpp v214, v52, v92 row_shl:14 row_mask:0xf bank_mask:0xf
	v_fmac_f32_dpp v215, v53, v93 row_shl:14 row_mask:0xf bank_mask:0xf
	v_fmac_f32_dpp v216, v54, v94 row_shl:14 row_mask:0xf bank_mask:0xf
	v_fmac_f32_dpp v217, v55, v95 row_shl:14 row_mask:0xf bank_mask:0xf
	v_exp_f32_e32 v218, v210
	v_exp_f32_e32 v219, v211
	v_exp_f32_e32 v220, v212
	v_exp_f32_e32 v221, v213
	v_exp_f32_e32 v222, v214
	v_exp_f32_e32 v223, v215
	v_exp_f32_e32 v224, v216
	v_exp_f32_e32 v225, v217
	v_add_f32_e32 v218, 1.0, v218
	v_add_f32_e32 v219, 1.0, v219
	v_add_f32_e32 v220, 1.0, v220
	v_add_f32_e32 v221, 1.0, v221
	v_add_f32_e32 v222, 1.0, v222
	v_add_f32_e32 v223, 1.0, v223
	v_add_f32_e32 v224, 1.0, v224
	v_add_f32_e32 v225, 1.0, v225
	v_rcp_f32_e32 v218, v218
	v_rcp_f32_e32 v219, v219
	v_rcp_f32_e32 v220, v220
	v_rcp_f32_e32 v221, v221
	v_rcp_f32_e32 v222, v222
	v_rcp_f32_e32 v223, v223
	v_rcp_f32_e32 v224, v224
	v_rcp_f32_e32 v225, v225
	v_mul_f32_e32 v36, v36, v207
	v_mul_f32_e32 v37, v37, v207
	v_mul_f32_e32 v38, v38, v207
	v_mul_f32_e32 v39, v39, v207
	v_mul_f32_e32 v32, v32, v207
	v_mul_f32_e32 v33, v33, v207
;     __device__ __forceinline__ void operator()(const Acc& acc, const Unit& u, int wr, int wc, int fr, int fq, LAS unsigned char* lds, f32x4 epar) const {
;     ...
;             for (int m = 0; m < 4; ++m) {
;                 const int r = u.pm * BM + ai * HALF + wr * 64 + m * 16 + fr;
;                 const float rs = __builtin_amdgcn_rsqf(sq[ai][m] * (1.0f / DM) + RMS_EPS);
;                 float X[NV], Y[NV], o[NV];
;                 if (MODE == 0) {
; #pragma unroll
;                     for (int n = 0; n < 2; ++n)
; #pragma unroll
;                         for (int j = 0; j < 4; ++j) { X[n * 4 + j] = acc[ai][0][m][n][j] * rs; Y[n * 4 + j] = acc[ai][1][m][n][j] * rs; }
;                 } else {
; #pragma unroll
;                     for (int j = 0; j < 4; ++j) { X[j] = (acc[ai][0][m][1][j] * rs) * (acc[ai][1][m][0][j] * rs); Y[j] = acc[ai][0][m][0][j] * rs; }
;                 }
; #pragma unroll
;                 for (int i = 0; i < NV; ++i) {
;                     const float a1 = dpp_rot<0x121>(X[i]), a2 = dpp_rot<0x122>(X[i]);
;                     const float q1 = fr >= 1 ? a1 : p1prev[i], q2 = fr >= 2 ? a2 : p2prev[i];
;                     p1prev[i] = a1; p2prev[i] = a2;
;                     const float cv = w2[i] * X[i] + w1[i] * q1 + w0[i] * q2 + bb[i];
;                     o[i] = MODE == 0 ? silu_f(cv) * Y[i] : cv * Y[i];
;                 }
;                 if (m == 0 && fr < 2) {
;                     bf16_t* hx = halo + ((size_t)strip * 6 + 2 + fr) * C + c0; bf16_t* hy = halo + ((size_t)strip * 6 + 4 + fr) * C + c0;
;                     u32x4 px, py; px.x = cvt_pk_bf16(X[0], X[1]); px.y = cvt_pk_bf16(X[2], X[3]); px.z = cvt_pk_bf16(X[4 % NV], X[5 % NV]); px.w = cvt_pk_bf16(X[6 % NV], X[7 % NV]);
;                     py.x = cvt_pk_bf16(Y[0], Y[1]); py.y = cvt_pk_bf16(Y[2], Y[3]); py.z = cvt_pk_bf16(Y[4 % NV], Y[5 % NV]); py.w = cvt_pk_bf16(Y[6 % NV], Y[7 % NV]);
;                     if (MODE == 0) { *(u32x4*)hx = px; *(u32x4*)hy = py; } else { u32x2 a; a.x = px.x; a.y = px.y; *(u32x2*)hx = a; u32x2 b; b.x = py.x; b.y = py.y; *(u32x2*)hy = b; }
;                 } else {
;                     if (MODE == 0) { u32x4 w; w.x = cvt_pk_bf16(o[0], o[1]); w.y = cvt_pk_bf16(o[2], o[3]); w.z = cvt_pk_bf16(o[4 % NV], o[5 % NV]); w.w = cvt_pk_bf16(o[6 % NV], o[7 % NV]);
	v_mul_f32_e32 v34, v34, v207
	v_mul_f32_e32 v35, v35, v207
	v_mul_f32_e32 v210, v210, v218
	v_mul_f32_e32 v211, v211, v219
	v_mul_f32_e32 v212, v212, v220
	v_mul_f32_e32 v213, v213, v221
	v_mul_f32_e32 v214, v214, v222
	v_mul_f32_e32 v215, v215, v223
	v_mul_f32_e32 v216, v216, v224
	v_mul_f32_e32 v217, v217, v225
	v_mul_f32_e32 v36, v210, v36
	v_mul_f32_e32 v37, v211, v37
	v_mul_f32_e32 v38, v212, v38
	v_mul_f32_e32 v39, v213, v39
	v_mul_f32_e32 v32, v214, v32
	v_mul_f32_e32 v33, v215, v33
	v_mul_f32_e32 v34, v216, v34
	v_mul_f32_e32 v35, v217, v35
	v_cvt_pk_bf16_f32 v226, v36, v37
	v_cvt_pk_bf16_f32 v227, v38, v39
	v_cvt_pk_bf16_f32 v228, v32, v33
	v_cvt_pk_bf16_f32 v229, v34, v35
	v_add_u32_e32 v234, 0xc6000, v230
	global_store_dwordx4 v234, v[226:229], s[96:97] nt
	v_mul_f32_e32 v28, v28, v78
	v_mul_f32_e32 v29, v29, v78
	v_mul_f32_e32 v30, v30, v78
	v_mul_f32_e32 v31, v31, v78
	v_mul_f32_e32 v24, v24, v78
	v_mul_f32_e32 v25, v25, v78
	v_mul_f32_e32 v26, v26, v78
	v_mul_f32_e32 v27, v27, v78
	v_fma_f32 v210, v28, v136, v174
	v_fma_f32 v211, v29, v137, v175
	v_fma_f32 v212, v30, v138, v176
	v_fma_f32 v213, v31, v139, v177
	v_fma_f32 v214, v24, v140, v178
	v_fma_f32 v215, v25, v141, v179
	v_fma_f32 v216, v26, v142, v180
	v_fma_f32 v217, v27, v143, v181
	v_fmac_f32_dpp v210, v28, v128 row_shr:1 row_mask:0xf bank_mask:0xf
	v_fmac_f32_dpp v211, v29, v129 row_shr:1 row_mask:0xf bank_mask:0xf
	v_fmac_f32_dpp v212, v30, v130 row_shr:1 row_mask:0xf bank_mask:0xf
	v_fmac_f32_dpp v213, v31, v131 row_shr:1 row_mask:0xf bank_mask:0xf
	v_fmac_f32_dpp v214, v24, v132 row_shr:1 row_mask:0xf bank_mask:0xf
	v_fmac_f32_dpp v215, v25, v133 row_shr:1 row_mask:0xf bank_mask:0xf
	v_fmac_f32_dpp v216, v26, v134 row_shr:1 row_mask:0xf bank_mask:0xf
	v_fmac_f32_dpp v217, v27, v135 row_shr:1 row_mask:0xf bank_mask:0xf
	v_fmac_f32_dpp v210, v28, v88 row_shr:2 row_mask:0xf bank_mask:0xf
	v_fmac_f32_dpp v211, v29, v89 row_shr:2 row_mask:0xf bank_mask:0xf
	v_fmac_f32_dpp v212, v30, v90 row_shr:2 row_mask:0xf bank_mask:0xf
	v_fmac_f32_dpp v213, v31, v91 row_shr:2 row_mask:0xf bank_mask:0xf
	v_fmac_f32_dpp v214, v24, v92 row_shr:2 row_mask:0xf bank_mask:0xf
	v_fmac_f32_dpp v215, v25, v93 row_shr:2 row_mask:0xf bank_mask:0xf
	v_fmac_f32_dpp v216, v26, v94 row_shr:2 row_mask:0xf bank_mask:0xf
	v_fmac_f32_dpp v217, v27, v95 row_shr:2 row_mask:0xf bank_mask:0xf
	v_fmac_f32_dpp v210, v44, v128 row_shl:15 row_mask:0xf bank_mask:0xf
	v_fmac_f32_dpp v211, v45, v129 row_shl:15 row_mask:0xf bank_mask:0xf
	v_fmac_f32_dpp v212, v46, v130 row_shl:15 row_mask:0xf bank_mask:0xf
	v_fmac_f32_dpp v213, v47, v131 row_shl:15 row_mask:0xf bank_mask:0xf
	v_fmac_f32_dpp v214, v40, v132 row_shl:15 row_mask:0xf bank_mask:0xf
	v_fmac_f32_dpp v215, v41, v133 row_shl:15 row_mask:0xf bank_mask:0xf
	v_fmac_f32_dpp v216, v42, v134 row_shl:15 row_mask:0xf bank_mask:0xf
	v_fmac_f32_dpp v217, v43, v135 row_shl:15 row_mask:0xf bank_mask:0xf
	v_fmac_f32_dpp v210, v44, v88 row_shl:14 row_mask:0xf bank_mask:0xf
	v_fmac_f32_dpp v211, v45, v89 row_shl:14 row_mask:0xf bank_mask:0xf
	v_fmac_f32_dpp v212, v46, v90 row_shl:14 row_mask:0xf bank_mask:0xf
	v_fmac_f32_dpp v213, v47, v91 row_shl:14 row_mask:0xf bank_mask:0xf
	v_fmac_f32_dpp v214, v40, v92 row_shl:14 row_mask:0xf bank_mask:0xf
	v_fmac_f32_dpp v215, v41, v93 row_shl:14 row_mask:0xf bank_mask:0xf
	v_fmac_f32_dpp v216, v42, v94 row_shl:14 row_mask:0xf bank_mask:0xf
	v_fmac_f32_dpp v217, v43, v95 row_shl:14 row_mask:0xf bank_mask:0xf
	v_exp_f32_e32 v218, v210
	v_exp_f32_e32 v219, v211
	v_exp_f32_e32 v220, v212
	v_exp_f32_e32 v221, v213
	v_exp_f32_e32 v222, v214
	v_exp_f32_e32 v223, v215
	v_exp_f32_e32 v224, v216
	v_exp_f32_e32 v225, v217
	v_add_f32_e32 v218, 1.0, v218
	v_add_f32_e32 v219, 1.0, v219
	v_add_f32_e32 v220, 1.0, v220
	v_add_f32_e32 v221, 1.0, v221
	v_add_f32_e32 v222, 1.0, v222
	v_add_f32_e32 v223, 1.0, v223
	v_add_f32_e32 v224, 1.0, v224
	v_add_f32_e32 v225, 1.0, v225
	v_rcp_f32_e32 v218, v218
	v_rcp_f32_e32 v219, v219
	v_rcp_f32_e32 v220, v220
	v_rcp_f32_e32 v221, v221
	v_rcp_f32_e32 v222, v222
	v_rcp_f32_e32 v223, v223
	v_rcp_f32_e32 v224, v224
	v_rcp_f32_e32 v225, v225
	v_mul_f32_e32 v20, v20, v208
	v_mul_f32_e32 v21, v21, v208
	v_mul_f32_e32 v22, v22, v208
	v_mul_f32_e32 v23, v23, v208
	v_mul_f32_e32 v16, v16, v208
	v_mul_f32_e32 v17, v17, v208
	v_mul_f32_e32 v18, v18, v208
	v_mul_f32_e32 v19, v19, v208
	v_mul_f32_e32 v210, v210, v218
	v_mul_f32_e32 v211, v211, v219
	v_mul_f32_e32 v212, v212, v220
	v_mul_f32_e32 v213, v213, v221
	v_mul_f32_e32 v214, v214, v222
	v_mul_f32_e32 v215, v215, v223
	v_mul_f32_e32 v216, v216, v224
	v_mul_f32_e32 v217, v217, v225
	v_mul_f32_e32 v20, v210, v20
	v_mul_f32_e32 v21, v211, v21
	v_mul_f32_e32 v22, v212, v22
	v_mul_f32_e32 v23, v213, v23
	v_mul_f32_e32 v16, v214, v16
	v_mul_f32_e32 v17, v215, v17
;     __device__ __forceinline__ void operator()(const Acc& acc, const Unit& u, int wr, int wc, int fr, int fq, LAS unsigned char* lds, f32x4 epar) const {
;     ...
;             for (int m = 0; m < 4; ++m) {
;                 const int r = u.pm * BM + ai * HALF + wr * 64 + m * 16 + fr;
;                 const float rs = __builtin_amdgcn_rsqf(sq[ai][m] * (1.0f / DM) + RMS_EPS);
;                 float X[NV], Y[NV], o[NV];
;                 if (MODE == 0) {
; #pragma unroll
;                     for (int n = 0; n < 2; ++n)
; #pragma unroll
;                         for (int j = 0; j < 4; ++j) { X[n * 4 + j] = acc[ai][0][m][n][j] * rs; Y[n * 4 + j] = acc[ai][1][m][n][j] * rs; }
;                 } else {
; #pragma unroll
;                     for (int j = 0; j < 4; ++j) { X[j] = (acc[ai][0][m][1][j] * rs) * (acc[ai][1][m][0][j] * rs); Y[j] = acc[ai][0][m][0][j] * rs; }
;                 }
; #pragma unroll
;                 for (int i = 0; i < NV; ++i) {
;                     const float a1 = dpp_rot<0x121>(X[i]), a2 = dpp_rot<0x122>(X[i]);
;                     const float q1 = fr >= 1 ? a1 : p1prev[i], q2 = fr >= 2 ? a2 : p2prev[i];
;                     p1prev[i] = a1; p2prev[i] = a2;
;                     const float cv = w2[i] * X[i] + w1[i] * q1 + w0[i] * q2 + bb[i];
;                     o[i] = MODE == 0 ? silu_f(cv) * Y[i] : cv * Y[i];
;                 }
;                 if (m == 0 && fr < 2) {
;                     bf16_t* hx = halo + ((size_t)strip * 6 + 2 + fr) * C + c0; bf16_t* hy = halo + ((size_t)strip * 6 + 4 + fr) * C + c0;
;                     u32x4 px, py; px.x = cvt_pk_bf16(X[0], X[1]); px.y = cvt_pk_bf16(X[2], X[3]); px.z = cvt_pk_bf16(X[4 % NV], X[5 % NV]); px.w = cvt_pk_bf16(X[6 % NV], X[7 % NV]);
;                     py.x = cvt_pk_bf16(Y[0], Y[1]); py.y = cvt_pk_bf16(Y[2], Y[3]); py.z = cvt_pk_bf16(Y[4 % NV], Y[5 % NV]); py.w = cvt_pk_bf16(Y[6 % NV], Y[7 % NV]);
;                     if (MODE == 0) { *(u32x4*)hx = px; *(u32x4*)hy = py; } else { u32x2 a; a.x = px.x; a.y = px.y; *(u32x2*)hx = a; u32x2 b; b.x = py.x; b.y = py.y; *(u32x2*)hy = b; }
;                 } else {
;                     if (MODE == 0) { u32x4 w; w.x = cvt_pk_bf16(o[0], o[1]); w.y = cvt_pk_bf16(o[2], o[3]); w.z = cvt_pk_bf16(o[4 % NV], o[5 % NV]); w.w = cvt_pk_bf16(o[6 % NV], o[7 % NV]);
	v_mul_f32_e32 v18, v216, v18
	v_mul_f32_e32 v19, v217, v19
	v_cvt_pk_bf16_f32 v226, v20, v21
	v_cvt_pk_bf16_f32 v227, v22, v23
	v_cvt_pk_bf16_f32 v228, v16, v17
	v_cvt_pk_bf16_f32 v229, v18, v19
	v_add_u32_e32 v234, 0xdc000, v230
	global_store_dwordx4 v234, v[226:229], s[96:97] nt
	v_mul_f32_e32 v12, v12, v79
	v_mul_f32_e32 v13, v13, v79
	v_mul_f32_e32 v14, v14, v79
	v_mul_f32_e32 v15, v15, v79
	v_mul_f32_e32 v8, v8, v79
	v_mul_f32_e32 v9, v9, v79
	v_mul_f32_e32 v10, v10, v79
	v_mul_f32_e32 v11, v11, v79
	v_fma_f32 v210, v12, v136, v174
	v_fma_f32 v211, v13, v137, v175
	v_fma_f32 v212, v14, v138, v176
	v_fma_f32 v213, v15, v139, v177
	v_fma_f32 v214, v8, v140, v178
	v_fma_f32 v215, v9, v141, v179
	v_fma_f32 v216, v10, v142, v180
	v_fma_f32 v217, v11, v143, v181
	v_cvt_pk_bf16_f32 v236, v12, v13
	v_cvt_pk_bf16_f32 v237, v14, v15
	v_cvt_pk_bf16_f32 v238, v8, v9
	v_cvt_pk_bf16_f32 v239, v10, v11
	v_add_u32_e32 v235, 0xffffd400, v233
	s_and_b64 exec, exec, s[10:11]
	global_store_dwordx4 v235, v[236:239], s[42:43]
	s_mov_b64 exec, s[24:25]
	v_fmac_f32_dpp v210, v12, v128 row_shr:1 row_mask:0xf bank_mask:0xf
	v_fmac_f32_dpp v211, v13, v129 row_shr:1 row_mask:0xf bank_mask:0xf
	v_fmac_f32_dpp v212, v14, v130 row_shr:1 row_mask:0xf bank_mask:0xf
	v_fmac_f32_dpp v213, v15, v131 row_shr:1 row_mask:0xf bank_mask:0xf
	v_fmac_f32_dpp v214, v8, v132 row_shr:1 row_mask:0xf bank_mask:0xf
	v_fmac_f32_dpp v215, v9, v133 row_shr:1 row_mask:0xf bank_mask:0xf
	v_fmac_f32_dpp v216, v10, v134 row_shr:1 row_mask:0xf bank_mask:0xf
	v_fmac_f32_dpp v217, v11, v135 row_shr:1 row_mask:0xf bank_mask:0xf
	v_fmac_f32_dpp v210, v12, v88 row_shr:2 row_mask:0xf bank_mask:0xf
	v_fmac_f32_dpp v211, v13, v89 row_shr:2 row_mask:0xf bank_mask:0xf
	v_fmac_f32_dpp v212, v14, v90 row_shr:2 row_mask:0xf bank_mask:0xf
	v_fmac_f32_dpp v213, v15, v91 row_shr:2 row_mask:0xf bank_mask:0xf
	v_fmac_f32_dpp v214, v8, v92 row_shr:2 row_mask:0xf bank_mask:0xf
	v_fmac_f32_dpp v215, v9, v93 row_shr:2 row_mask:0xf bank_mask:0xf
	v_fmac_f32_dpp v216, v10, v94 row_shr:2 row_mask:0xf bank_mask:0xf
	v_fmac_f32_dpp v217, v11, v95 row_shr:2 row_mask:0xf bank_mask:0xf
	v_fmac_f32_dpp v210, v28, v128 row_shl:15 row_mask:0xf bank_mask:0xf
	v_fmac_f32_dpp v211, v29, v129 row_shl:15 row_mask:0xf bank_mask:0xf
	v_fmac_f32_dpp v212, v30, v130 row_shl:15 row_mask:0xf bank_mask:0xf
	v_fmac_f32_dpp v213, v31, v131 row_shl:15 row_mask:0xf bank_mask:0xf
	v_fmac_f32_dpp v214, v24, v132 row_shl:15 row_mask:0xf bank_mask:0xf
	v_fmac_f32_dpp v215, v25, v133 row_shl:15 row_mask:0xf bank_mask:0xf
	v_fmac_f32_dpp v216, v26, v134 row_shl:15 row_mask:0xf bank_mask:0xf
	v_fmac_f32_dpp v217, v27, v135 row_shl:15 row_mask:0xf bank_mask:0xf
	v_fmac_f32_dpp v210, v28, v88 row_shl:14 row_mask:0xf bank_mask:0xf
	v_fmac_f32_dpp v211, v29, v89 row_shl:14 row_mask:0xf bank_mask:0xf
	v_fmac_f32_dpp v212, v30, v90 row_shl:14 row_mask:0xf bank_mask:0xf
	v_fmac_f32_dpp v213, v31, v91 row_shl:14 row_mask:0xf bank_mask:0xf
	v_fmac_f32_dpp v214, v24, v92 row_shl:14 row_mask:0xf bank_mask:0xf
	v_fmac_f32_dpp v215, v25, v93 row_shl:14 row_mask:0xf bank_mask:0xf
	v_fmac_f32_dpp v216, v26, v94 row_shl:14 row_mask:0xf bank_mask:0xf
	v_fmac_f32_dpp v217, v27, v95 row_shl:14 row_mask:0xf bank_mask:0xf
	v_exp_f32_e32 v218, v210
	v_exp_f32_e32 v219, v211
	v_exp_f32_e32 v220, v212
	v_exp_f32_e32 v221, v213
	v_exp_f32_e32 v222, v214
	v_exp_f32_e32 v223, v215
	v_exp_f32_e32 v224, v216
	v_exp_f32_e32 v225, v217
	v_add_f32_e32 v218, 1.0, v218
	v_add_f32_e32 v219, 1.0, v219
	v_add_f32_e32 v220, 1.0, v220
	v_add_f32_e32 v221, 1.0, v221
	v_add_f32_e32 v222, 1.0, v222
	v_add_f32_e32 v223, 1.0, v223
	v_add_f32_e32 v224, 1.0, v224
	v_add_f32_e32 v225, 1.0, v225
	v_rcp_f32_e32 v218, v218
	v_rcp_f32_e32 v219, v219
	v_rcp_f32_e32 v220, v220
	v_rcp_f32_e32 v221, v221
	v_rcp_f32_e32 v222, v222
	v_rcp_f32_e32 v223, v223
	v_rcp_f32_e32 v224, v224
	v_rcp_f32_e32 v225, v225
	v_mul_f32_e32 v4, v4, v209
	v_mul_f32_e32 v5, v5, v209
	v_mul_f32_e32 v6, v6, v209
	v_mul_f32_e32 v7, v7, v209
	v_mul_f32_e32 v0, v0, v209
	v_mul_f32_e32 v1, v1, v209
	v_mul_f32_e32 v2, v2, v209
	v_mul_f32_e32 v3, v3, v209
	v_mul_f32_e32 v210, v210, v218
	v_mul_f32_e32 v211, v211, v219
	v_mul_f32_e32 v212, v212, v220
	v_mul_f32_e32 v213, v213, v221
	v_mul_f32_e32 v214, v214, v222
	v_mul_f32_e32 v215, v215, v223
	v_mul_f32_e32 v216, v216, v224
	v_mul_f32_e32 v217, v217, v225
	v_mul_f32_e32 v4, v210, v4
	v_mul_f32_e32 v5, v211, v5
	v_mul_f32_e32 v6, v212, v6
	v_mul_f32_e32 v7, v213, v7
	v_mul_f32_e32 v0, v214, v0
	v_mul_f32_e32 v1, v215, v1
	v_mul_f32_e32 v2, v216, v2
	v_mul_f32_e32 v3, v217, v3
	v_cvt_pk_bf16_f32 v226, v4, v5
	v_cvt_pk_bf16_f32 v227, v6, v7
	v_cvt_pk_bf16_f32 v228, v0, v1
	v_cvt_pk_bf16_f32 v229, v2, v3
	v_add_u32_e32 v234, 0xf2000, v230
	global_store_dwordx4 v234, v[226:229], s[96:97] nt

;     __device__ __forceinline__ void operator()(const Acc& acc, const Unit& u, int wr, int wc, int fr, int fq, LAS unsigned char* lds, f32x4 epar) const {
;     ...
;         LAS float* pw = (LAS float*)(lds + STAGE_BYTES + 64 + (wr * 4 + wc) * 1024);
;         *(LAS f32x4*)(pw + (fq * 16 + fr) * 4) = epar;
;         asm volatile("s_waitcnt lgkmcnt(0)" ::: "memory");
;         float w0[NV], w1[NV], w2[NV], bb[NV];
; #pragma unroll
;         for (int i = 0; i < NV; i += 4) { const f32x4 a = *(const LAS f32x4*)(pw + NV * fq + i), b = *(const LAS f32x4*)(pw + 32 + NV * fq + i), c = *(const LAS f32x4*)(pw + 64 + NV * fq + i);
;             f32x4 d = (f32x4){0.f, 0.f, 0.f, 0.f}; if (MODE == 0) d = *(const LAS f32x4*)(pw + 96 + NV * fq + i);
; #pragma unroll
;             for (int j = 0; j < 4; ++j) { w0[i + j] = a[j]; w1[i + j] = b[j]; w2[i + j] = c[j]; bb[i + j] = d[j]; } }
;         float sq[2][4];
; #pragma unroll
;         for (int ai = 0; ai < 2; ++ai)
; #pragma unroll
;             for (int m = 0; m < 4; ++m) sq[ai][m] = pw[128 + ai * 64 + m * 16 + fr];
; #pragma unroll
;         for (int ai = 0; ai < 2; ++ai) {
;             const int strip = u.pm * 4 + ai * 2 + wr;
;             float p1prev[NV], p2prev[NV];
; #pragma unroll
;             for (int i = 0; i < NV; ++i) { p1prev[i] = 0.f; p2prev[i] = 0.f; }
; #pragma unroll
;             for (int m = 0; m < 4; ++m) {
;                 const int r = u.pm * BM + ai * HALF + wr * 64 + m * 16 + fr;
;                 const float rs = __builtin_amdgcn_rsqf(sq[ai][m] * (1.0f / DM) + RMS_EPS);
;                 float X[NV], Y[NV], o[NV];
;                 if (MODE == 0) {
; #pragma unroll
;                     for (int n = 0; n < 2; ++n)
; #pragma unroll
;                         for (int j = 0; j < 4; ++j) { X[n * 4 + j] = acc[ai][0][m][n][j] * rs; Y[n * 4 + j] = acc[ai][1][m][n][j] * rs; }
;                 } else {
; #pragma unroll
;                     for (int j = 0; j < 4; ++j) { X[j] = (acc[ai][0][m][1][j] * rs) * (acc[ai][1][m][0][j] * rs); Y[j] = acc[ai][0][m][0][j] * rs; }
;                 }
; #pragma unroll
;                 for (int i = 0; i < NV; ++i) {
;                     const float a1 = dpp_rot<0x121>(X[i]), a2 = dpp_rot<0x122>(X[i]);
;                     const float q1 = fr >= 1 ? a1 : p1prev[i], q2 = fr >= 2 ? a2 : p2prev[i];
;                     p1prev[i] = a1; p2prev[i] = a2;
.LBB0_986:
	ds_write_b128 v198, v[72:75]
	s_mov_b64 s[24:25], exec
	s_waitcnt lgkmcnt(0)
	ds_read_b128 v[88:91], v199
	ds_read_b128 v[92:95], v199 offset:16
	ds_read_b128 v[128:131], v199 offset:128
	ds_read_b128 v[132:135], v199 offset:144
	ds_read_b128 v[136:139], v199 offset:256
	ds_read_b128 v[140:143], v199 offset:272
	ds_read_b128 v[174:177], v199 offset:384
	ds_read_b128 v[178:181], v199 offset:400
	ds_read2_b32 v[182:183], v191 offset0:128 offset1:144
	ds_read2_b32 v[184:185], v191 offset0:160 offset1:176
	ds_read2_b32 v[76:77], v191 offset0:192 offset1:208
	ds_read2_b32 v[78:79], v191 offset0:224 offset1:240
	v_lshl_add_u32 v230, s66, 8, v190
	v_lshl_or_b32 v231, s70, 7, v192
	v_mul_u32_u24_e32 v230, 0x1600, v230
	s_lshl_b32 s26, s66, 2
	s_add_i32 s26, s26, s15
	s_mul_i32 s16, s26, 6
	v_and_b32_e32 v233, 15, v190
	v_lshl_add_u32 v230, v231, 1, v230
	v_add_u32_e32 v233, s16, v233
	v_mul_u32_u24_e32 v233, 0x1600, v233
	s_nop 0
	v_lshl_add_u32 v233, v231, 1, v233
	s_waitcnt lgkmcnt(0)
	v_mul_f32_e32 v88, 0xbfb8aa3b, v88
	v_mul_f32_e32 v89, 0xbfb8aa3b, v89
	v_mul_f32_e32 v90, 0xbfb8aa3b, v90
	v_mul_f32_e32 v91, 0xbfb8aa3b, v91
	v_mul_f32_e32 v92, 0xbfb8aa3b, v92
	v_mul_f32_e32 v93, 0xbfb8aa3b, v93
	v_mul_f32_e32 v94, 0xbfb8aa3b, v94
	v_mul_f32_e32 v95, 0xbfb8aa3b, v95
	v_mul_f32_e32 v128, 0xbfb8aa3b, v128
	v_mul_f32_e32 v129, 0xbfb8aa3b, v129
	v_mul_f32_e32 v130, 0xbfb8aa3b, v130
	v_mul_f32_e32 v131, 0xbfb8aa3b, v131
	v_mul_f32_e32 v132, 0xbfb8aa3b, v132
	v_mul_f32_e32 v133, 0xbfb8aa3b, v133
	v_mul_f32_e32 v134, 0xbfb8aa3b, v134
	v_mul_f32_e32 v135, 0xbfb8aa3b, v135
	v_mul_f32_e32 v136, 0xbfb8aa3b, v136
	v_mul_f32_e32 v137, 0xbfb8aa3b, v137
	v_mul_f32_e32 v138, 0xbfb8aa3b, v138
	v_mul_f32_e32 v139, 0xbfb8aa3b, v139
	v_mul_f32_e32 v140, 0xbfb8aa3b, v140
	v_mul_f32_e32 v141, 0xbfb8aa3b, v141
	v_mul_f32_e32 v142, 0xbfb8aa3b, v142
	v_mul_f32_e32 v143, 0xbfb8aa3b, v143
	v_mul_f32_e32 v174, 0xbfb8aa3b, v174
	v_mul_f32_e32 v175, 0xbfb8aa3b, v175
	v_mul_f32_e32 v176, 0xbfb8aa3b, v176
	v_mul_f32_e32 v177, 0xbfb8aa3b, v177
	v_mul_f32_e32 v178, 0xbfb8aa3b, v178
	v_mul_f32_e32 v179, 0xbfb8aa3b, v179
	v_mul_f32_e32 v180, 0xbfb8aa3b, v180
	v_mul_f32_e32 v181, 0xbfb8aa3b, v181
	v_fmamk_f32 v182, v182, 0x3a800000, v200
	v_fmamk_f32 v183, v183, 0x3a800000, v200
	v_fmamk_f32 v184, v184, 0x3a800000, v200
	v_fmamk_f32 v185, v185, 0x3a800000, v200
	v_fmamk_f32 v76, v76, 0x3a800000, v200
	v_fmamk_f32 v77, v77, 0x3a800000, v200
	v_fmamk_f32 v78, v78, 0x3a800000, v200
	v_fmamk_f32 v79, v79, 0x3a800000, v200
	v_rsq_f32_e32 v182, v182
	v_rsq_f32_e32 v183, v183
	v_rsq_f32_e32 v184, v184
	v_rsq_f32_e32 v185, v185
	v_rsq_f32_e32 v76, v76
	v_rsq_f32_e32 v77, v77
	v_rsq_f32_e32 v78, v78
	v_rsq_f32_e32 v79, v79
	s_nop 0
	v_mul_f32_e32 v202, 0xbf317218, v182
	v_mul_f32_e32 v203, 0xbf317218, v183
	v_mul_f32_e32 v204, 0xbf317218, v184
	v_mul_f32_e32 v205, 0xbf317218, v185
	v_mul_f32_e32 v206, 0xbf317218, v76
	v_mul_f32_e32 v207, 0xbf317218, v77
	v_mul_f32_e32 v208, 0xbf317218, v78
	v_mul_f32_e32 v209, 0xbf317218, v79
	v_mul_f32_e32 v152, v152, v182
	v_mul_f32_e32 v153, v153, v182
	v_mul_f32_e32 v154, v154, v182
	v_mul_f32_e32 v155, v155, v182
	v_mul_f32_e32 v144, v144, v182
	v_mul_f32_e32 v145, v145, v182
	v_mul_f32_e32 v146, v146, v182
	v_mul_f32_e32 v147, v147, v182
	v_fma_f32 v210, v152, v136, v174
	v_fma_f32 v211, v153, v137, v175
	v_fma_f32 v212, v154, v138, v176
	v_fma_f32 v213, v155, v139, v177
	v_fma_f32 v214, v144, v140, v178
	v_fma_f32 v215, v145, v141, v179
	v_fma_f32 v216, v146, v142, v180
	v_fma_f32 v217, v147, v143, v181
	v_mul_f32_e32 v218, v156, v182
	v_mul_f32_e32 v219, v157, v182
	v_mul_f32_e32 v220, v158, v182
	v_mul_f32_e32 v221, v159, v182
	v_mul_f32_e32 v222, v148, v182
	v_mul_f32_e32 v223, v149, v182
	v_mul_f32_e32 v224, v150, v182
	v_mul_f32_e32 v225, v151, v182
	v_cvt_pk_bf16_f32 v236, v152, v153
	v_cvt_pk_bf16_f32 v237, v154, v155
	v_cvt_pk_bf16_f32 v238, v144, v145
	v_cvt_pk_bf16_f32 v239, v146, v147
	v_cvt_pk_bf16_f32 v240, v218, v219
	v_cvt_pk_bf16_f32 v241, v220, v221
	v_cvt_pk_bf16_f32 v242, v222, v223
	v_cvt_pk_bf16_f32 v243, v224, v225
	v_add_u32_e32 v234, 0x2c00, v233
	v_add_u32_e32 v235, 0x5800, v233
	s_andn2_b64 exec, exec, s[8:9]
	global_store_dwordx4 v234, v[236:239], s[42:43]
	global_store_dwordx4 v235, v[240:243], s[42:43]
	s_mov_b64 exec, s[24:25]
	v_fmac_f32_dpp v210, v152, v128 row_shr:1 row_mask:0xf bank_mask:0xf
	v_fmac_f32_dpp v211, v153, v129 row_shr:1 row_mask:0xf bank_mask:0xf
	v_fmac_f32_dpp v212, v154, v130 row_shr:1 row_mask:0xf bank_mask:0xf
	v_fmac_f32_dpp v213, v155, v131 row_shr:1 row_mask:0xf bank_mask:0xf
	v_fmac_f32_dpp v214, v144, v132 row_shr:1 row_mask:0xf bank_mask:0xf
	v_fmac_f32_dpp v215, v145, v133 row_shr:1 row_mask:0xf bank_mask:0xf
	v_fmac_f32_dpp v216, v146, v134 row_shr:1 row_mask:0xf bank_mask:0xf
	v_fmac_f32_dpp v217, v147, v135 row_shr:1 row_mask:0xf bank_mask:0xf
	v_fmac_f32_dpp v210, v152, v88 row_shr:2 row_mask:0xf bank_mask:0xf
	v_fmac_f32_dpp v211, v153, v89 row_shr:2 row_mask:0xf bank_mask:0xf
	v_fmac_f32_dpp v212, v154, v90 row_shr:2 row_mask:0xf bank_mask:0xf
	v_fmac_f32_dpp v213, v155, v91 row_shr:2 row_mask:0xf bank_mask:0xf
	v_fmac_f32_dpp v214, v144, v92 row_shr:2 row_mask:0xf bank_mask:0xf
	v_fmac_f32_dpp v215, v145, v93 row_shr:2 row_mask:0xf bank_mask:0xf
	v_fmac_f32_dpp v216, v146, v94 row_shr:2 row_mask:0xf bank_mask:0xf
	v_fmac_f32_dpp v217, v147, v95 row_shr:2 row_mask:0xf bank_mask:0xf
	v_exp_f32_e32 v218, v210
	v_exp_f32_e32 v219, v211
	v_exp_f32_e32 v220, v212
	v_exp_f32_e32 v221, v213
	v_exp_f32_e32 v222, v214
	v_exp_f32_e32 v223, v215
	v_exp_f32_e32 v224, v216
;     __device__ __forceinline__ void operator()(const Acc& acc, const Unit& u, int wr, int wc, int fr, int fq, LAS unsigned char* lds, f32x4 epar) const {
;     ...
;             for (int m = 0; m < 4; ++m) {
;                 const int r = u.pm * BM + ai * HALF + wr * 64 + m * 16 + fr;
;                 const float rs = __builtin_amdgcn_rsqf(sq[ai][m] * (1.0f / DM) + RMS_EPS);
;                 float X[NV], Y[NV], o[NV];
;                 if (MODE == 0) {
; #pragma unroll
;                     for (int n = 0; n < 2; ++n)
; #pragma unroll
;                         for (int j = 0; j < 4; ++j) { X[n * 4 + j] = acc[ai][0][m][n][j] * rs; Y[n * 4 + j] = acc[ai][1][m][n][j] * rs; }
;                 } else {
; #pragma unroll
;                     for (int j = 0; j < 4; ++j) { X[j] = (acc[ai][0][m][1][j] * rs) * (acc[ai][1][m][0][j] * rs); Y[j] = acc[ai][0][m][0][j] * rs; }
;                 }
; #pragma unroll
;                 for (int i = 0; i < NV; ++i) {
;                     const float a1 = dpp_rot<0x121>(X[i]), a2 = dpp_rot<0x122>(X[i]);
;                     const float q1 = fr >= 1 ? a1 : p1prev[i], q2 = fr >= 2 ? a2 : p2prev[i];
;                     p1prev[i] = a1; p2prev[i] = a2;
;                     const float cv = w2[i] * X[i] + w1[i] * q1 + w0[i] * q2 + bb[i];
;                     o[i] = MODE == 0 ? silu_f(cv) * Y[i] : cv * Y[i];
;                 }
;                 if (m == 0 && fr < 2) {
;                     bf16_t* hx = halo + ((size_t)strip * 6 + 2 + fr) * C + c0; bf16_t* hy = halo + ((size_t)strip * 6 + 4 + fr) * C + c0;
;                     u32x4 px, py; px.x = cvt_pk_bf16(X[0], X[1]); px.y = cvt_pk_bf16(X[2], X[3]); px.z = cvt_pk_bf16(X[4 % NV], X[5 % NV]); px.w = cvt_pk_bf16(X[6 % NV], X[7 % NV]);
;                     py.x = cvt_pk_bf16(Y[0], Y[1]); py.y = cvt_pk_bf16(Y[2], Y[3]); py.z = cvt_pk_bf16(Y[4 % NV], Y[5 % NV]); py.w = cvt_pk_bf16(Y[6 % NV], Y[7 % NV]);
;                     if (MODE == 0) { *(u32x4*)hx = px; *(u32x4*)hy = py; } else { u32x2 a; a.x = px.x; a.y = px.y; *(u32x2*)hx = a; u32x2 b; b.x = py.x; b.y = py.y; *(u32x2*)hy = b; }
;                 } else {
;                     if (MODE == 0) { u32x4 w; w.x = cvt_pk_bf16(o[0], o[1]); w.y = cvt_pk_bf16(o[2], o[3]); w.z = cvt_pk_bf16(o[4 % NV], o[5 % NV]); w.w = cvt_pk_bf16(o[6 % NV], o[7 % NV]);
	v_exp_f32_e32 v225, v217
	v_add_f32_e32 v218, 1.0, v218
	v_add_f32_e32 v219, 1.0, v219
	v_add_f32_e32 v220, 1.0, v220
	v_add_f32_e32 v221, 1.0, v221
	v_add_f32_e32 v222, 1.0, v222
	v_add_f32_e32 v223, 1.0, v223
	v_add_f32_e32 v224, 1.0, v224
	v_add_f32_e32 v225, 1.0, v225
	v_rcp_f32_e32 v218, v218
	v_rcp_f32_e32 v219, v219
	v_rcp_f32_e32 v220, v220
	v_rcp_f32_e32 v221, v221
	v_rcp_f32_e32 v222, v222
	v_rcp_f32_e32 v223, v223
	v_rcp_f32_e32 v224, v224
	v_rcp_f32_e32 v225, v225
	v_mul_f32_e32 v156, v156, v202
	v_mul_f32_e32 v157, v157, v202
	v_mul_f32_e32 v158, v158, v202
	v_mul_f32_e32 v159, v159, v202
	v_mul_f32_e32 v148, v148, v202
	v_mul_f32_e32 v149, v149, v202
	v_mul_f32_e32 v150, v150, v202
	v_mul_f32_e32 v151, v151, v202
	v_mul_f32_e32 v210, v210, v218
	v_mul_f32_e32 v211, v211, v219
	v_mul_f32_e32 v212, v212, v220
	v_mul_f32_e32 v213, v213, v221
	v_mul_f32_e32 v214, v214, v222
	v_mul_f32_e32 v215, v215, v223
	v_mul_f32_e32 v216, v216, v224
	v_mul_f32_e32 v217, v217, v225
	v_mul_f32_e32 v156, v210, v156
	v_mul_f32_e32 v157, v211, v157
	v_mul_f32_e32 v158, v212, v158
	v_mul_f32_e32 v159, v213, v159
	v_mul_f32_e32 v148, v214, v148
	v_mul_f32_e32 v149, v215, v149
	v_mul_f32_e32 v150, v216, v150
	v_mul_f32_e32 v151, v217, v151
	v_cvt_pk_bf16_f32 v226, v156, v157
	v_cvt_pk_bf16_f32 v227, v158, v159
	v_cvt_pk_bf16_f32 v228, v148, v149
	v_cvt_pk_bf16_f32 v229, v150, v151
	v_add_u32_e32 v234, 0x0, v230
	s_and_b64 exec, exec, s[8:9]
	global_store_dwordx4 v234, v[226:229], s[96:97] nt
	s_mov_b64 exec, s[24:25]
	v_mul_f32_e32 v124, v124, v183
	v_mul_f32_e32 v125, v125, v183
	v_mul_f32_e32 v126, v126, v183
	v_mul_f32_e32 v127, v127, v183
	v_mul_f32_e32 v120, v120, v183
	v_mul_f32_e32 v121, v121, v183
	v_mul_f32_e32 v122, v122, v183
	v_mul_f32_e32 v123, v123, v183
	v_fma_f32 v210, v124, v136, v174
	v_fma_f32 v211, v125, v137, v175
	v_fma_f32 v212, v126, v138, v176
	v_fma_f32 v213, v127, v139, v177
	v_fma_f32 v214, v120, v140, v178
	v_fma_f32 v215, v121, v141, v179
	v_fma_f32 v216, v122, v142, v180
	v_fma_f32 v217, v123, v143, v181
	v_fmac_f32_dpp v210, v124, v128 row_shr:1 row_mask:0xf bank_mask:0xf
	v_fmac_f32_dpp v211, v125, v129 row_shr:1 row_mask:0xf bank_mask:0xf
	v_fmac_f32_dpp v212, v126, v130 row_shr:1 row_mask:0xf bank_mask:0xf
	v_fmac_f32_dpp v213, v127, v131 row_shr:1 row_mask:0xf bank_mask:0xf
	v_fmac_f32_dpp v214, v120, v132 row_shr:1 row_mask:0xf bank_mask:0xf
	v_fmac_f32_dpp v215, v121, v133 row_shr:1 row_mask:0xf bank_mask:0xf
	v_fmac_f32_dpp v216, v122, v134 row_shr:1 row_mask:0xf bank_mask:0xf
	v_fmac_f32_dpp v217, v123, v135 row_shr:1 row_mask:0xf bank_mask:0xf
	v_fmac_f32_dpp v210, v124, v88 row_shr:2 row_mask:0xf bank_mask:0xf
	v_fmac_f32_dpp v211, v125, v89 row_shr:2 row_mask:0xf bank_mask:0xf
	v_fmac_f32_dpp v212, v126, v90 row_shr:2 row_mask:0xf bank_mask:0xf
	v_fmac_f32_dpp v213, v127, v91 row_shr:2 row_mask:0xf bank_mask:0xf
	v_fmac_f32_dpp v214, v120, v92 row_shr:2 row_mask:0xf bank_mask:0xf
	v_fmac_f32_dpp v215, v121, v93 row_shr:2 row_mask:0xf bank_mask:0xf
	v_fmac_f32_dpp v216, v122, v94 row_shr:2 row_mask:0xf bank_mask:0xf
	v_fmac_f32_dpp v217, v123, v95 row_shr:2 row_mask:0xf bank_mask:0xf
	v_fmac_f32_dpp v210, v152, v128 row_shl:15 row_mask:0xf bank_mask:0xf
	v_fmac_f32_dpp v211, v153, v129 row_shl:15 row_mask:0xf bank_mask:0xf
	v_fmac_f32_dpp v212, v154, v130 row_shl:15 row_mask:0xf bank_mask:0xf
	v_fmac_f32_dpp v213, v155, v131 row_shl:15 row_mask:0xf bank_mask:0xf
	v_fmac_f32_dpp v214, v144, v132 row_shl:15 row_mask:0xf bank_mask:0xf
	v_fmac_f32_dpp v215, v145, v133 row_shl:15 row_mask:0xf bank_mask:0xf
	v_fmac_f32_dpp v216, v146, v134 row_shl:15 row_mask:0xf bank_mask:0xf
	v_fmac_f32_dpp v217, v147, v135 row_shl:15 row_mask:0xf bank_mask:0xf
	v_fmac_f32_dpp v210, v152, v88 row_shl:14 row_mask:0xf bank_mask:0xf
	v_fmac_f32_dpp v211, v153, v89 row_shl:14 row_mask:0xf bank_mask:0xf
	v_fmac_f32_dpp v212, v154, v90 row_shl:14 row_mask:0xf bank_mask:0xf
	v_fmac_f32_dpp v213, v155, v91 row_shl:14 row_mask:0xf bank_mask:0xf
	v_fmac_f32_dpp v214, v144, v92 row_shl:14 row_mask:0xf bank_mask:0xf
	v_fmac_f32_dpp v215, v145, v93 row_shl:14 row_mask:0xf bank_mask:0xf
	v_fmac_f32_dpp v216, v146, v94 row_shl:14 row_mask:0xf bank_mask:0xf
	v_fmac_f32_dpp v217, v147, v95 row_shl:14 row_mask:0xf bank_mask:0xf
	v_exp_f32_e32 v218, v210
	v_exp_f32_e32 v219, v211
	v_exp_f32_e32 v220, v212
	v_exp_f32_e32 v221, v213
	v_exp_f32_e32 v222, v214
	v_exp_f32_e32 v223, v215
	v_exp_f32_e32 v224, v216
	v_exp_f32_e32 v225, v217
	v_add_f32_e32 v218, 1.0, v218
	v_add_f32_e32 v219, 1.0, v219
	v_add_f32_e32 v220, 1.0, v220
	v_add_f32_e32 v221, 1.0, v221
	v_add_f32_e32 v222, 1.0, v222
	v_add_f32_e32 v223, 1.0, v223
	v_add_f32_e32 v224, 1.0, v224
	v_add_f32_e32 v225, 1.0, v225
	v_rcp_f32_e32 v218, v218
	v_rcp_f32_e32 v219, v219
	v_rcp_f32_e32 v220, v220
	v_rcp_f32_e32 v221, v221
	v_rcp_f32_e32 v222, v222
	v_rcp_f32_e32 v223, v223
	v_rcp_f32_e32 v224, v224
	v_rcp_f32_e32 v225, v225
	v_mul_f32_e32 v116, v116, v203
	v_mul_f32_e32 v117, v117, v203
	v_mul_f32_e32 v118, v118, v203
	v_mul_f32_e32 v119, v119, v203
	v_mul_f32_e32 v112, v112, v203
	v_mul_f32_e32 v113, v113, v203
	v_mul_f32_e32 v114, v114, v203
	v_mul_f32_e32 v115, v115, v203
	v_mul_f32_e32 v210, v210, v218
	v_mul_f32_e32 v211, v211, v219
	v_mul_f32_e32 v212, v212, v220
	v_mul_f32_e32 v213, v213, v221
	v_mul_f32_e32 v214, v214, v222
	v_mul_f32_e32 v215, v215, v223
	v_mul_f32_e32 v216, v216, v224
	v_mul_f32_e32 v217, v217, v225
	v_mul_f32_e32 v116, v210, v116
	v_mul_f32_e32 v117, v211, v117
	v_mul_f32_e32 v118, v212, v118
	v_mul_f32_e32 v119, v213, v119
	v_mul_f32_e32 v112, v214, v112
;     __device__ __forceinline__ void operator()(const Acc& acc, const Unit& u, int wr, int wc, int fr, int fq, LAS unsigned char* lds, f32x4 epar) const {
;     ...
;             for (int m = 0; m < 4; ++m) {
;                 const int r = u.pm * BM + ai * HALF + wr * 64 + m * 16 + fr;
;                 const float rs = __builtin_amdgcn_rsqf(sq[ai][m] * (1.0f / DM) + RMS_EPS);
;                 float X[NV], Y[NV], o[NV];
;                 if (MODE == 0) {
; #pragma unroll
;                     for (int n = 0; n < 2; ++n)
; #pragma unroll
;                         for (int j = 0; j < 4; ++j) { X[n * 4 + j] = acc[ai][0][m][n][j] * rs; Y[n * 4 + j] = acc[ai][1][m][n][j] * rs; }
;                 } else {
; #pragma unroll
;                     for (int j = 0; j < 4; ++j) { X[j] = (acc[ai][0][m][1][j] * rs) * (acc[ai][1][m][0][j] * rs); Y[j] = acc[ai][0][m][0][j] * rs; }
;                 }
; #pragma unroll
;                 for (int i = 0; i < NV; ++i) {
;                     const float a1 = dpp_rot<0x121>(X[i]), a2 = dpp_rot<0x122>(X[i]);
;                     const float q1 = fr >= 1 ? a1 : p1prev[i], q2 = fr >= 2 ? a2 : p2prev[i];
;                     p1prev[i] = a1; p2prev[i] = a2;
;                     const float cv = w2[i] * X[i] + w1[i] * q1 + w0[i] * q2 + bb[i];
;                     o[i] = MODE == 0 ? silu_f(cv) * Y[i] : cv * Y[i];
;                 }
;                 if (m == 0 && fr < 2) {
;                     bf16_t* hx = halo + ((size_t)strip * 6 + 2 + fr) * C + c0; bf16_t* hy = halo + ((size_t)strip * 6 + 4 + fr) * C + c0;
;                     u32x4 px, py; px.x = cvt_pk_bf16(X[0], X[1]); px.y = cvt_pk_bf16(X[2], X[3]); px.z = cvt_pk_bf16(X[4 % NV], X[5 % NV]); px.w = cvt_pk_bf16(X[6 % NV], X[7 % NV]);
;                     py.x = cvt_pk_bf16(Y[0], Y[1]); py.y = cvt_pk_bf16(Y[2], Y[3]); py.z = cvt_pk_bf16(Y[4 % NV], Y[5 % NV]); py.w = cvt_pk_bf16(Y[6 % NV], Y[7 % NV]);
;                     if (MODE == 0) { *(u32x4*)hx = px; *(u32x4*)hy = py; } else { u32x2 a; a.x = px.x; a.y = px.y; *(u32x2*)hx = a; u32x2 b; b.x = py.x; b.y = py.y; *(u32x2*)hy = b; }
;                 } else {
;                     if (MODE == 0) { u32x4 w; w.x = cvt_pk_bf16(o[0], o[1]); w.y = cvt_pk_bf16(o[2], o[3]); w.z = cvt_pk_bf16(o[4 % NV], o[5 % NV]); w.w = cvt_pk_bf16(o[6 % NV], o[7 % NV]);
	v_mul_f32_e32 v113, v215, v113
	v_mul_f32_e32 v114, v216, v114
	v_mul_f32_e32 v115, v217, v115
	v_cvt_pk_bf16_f32 v226, v116, v117
	v_cvt_pk_bf16_f32 v227, v118, v119
	v_cvt_pk_bf16_f32 v228, v112, v113
	v_cvt_pk_bf16_f32 v229, v114, v115
	v_add_u32_e32 v234, 0x16000, v230
	global_store_dwordx4 v234, v[226:229], s[96:97] nt
	v_mul_f32_e32 v108, v108, v184
	v_mul_f32_e32 v109, v109, v184
	v_mul_f32_e32 v110, v110, v184
	v_mul_f32_e32 v111, v111, v184
	v_mul_f32_e32 v104, v104, v184
	v_mul_f32_e32 v105, v105, v184
	v_mul_f32_e32 v106, v106, v184
	v_mul_f32_e32 v107, v107, v184
	v_fma_f32 v210, v108, v136, v174
	v_fma_f32 v211, v109, v137, v175
	v_fma_f32 v212, v110, v138, v176
	v_fma_f32 v213, v111, v139, v177
	v_fma_f32 v214, v104, v140, v178
	v_fma_f32 v215, v105, v141, v179
	v_fma_f32 v216, v106, v142, v180
	v_fma_f32 v217, v107, v143, v181
	v_fmac_f32_dpp v210, v108, v128 row_shr:1 row_mask:0xf bank_mask:0xf
	v_fmac_f32_dpp v211, v109, v129 row_shr:1 row_mask:0xf bank_mask:0xf
	v_fmac_f32_dpp v212, v110, v130 row_shr:1 row_mask:0xf bank_mask:0xf
	v_fmac_f32_dpp v213, v111, v131 row_shr:1 row_mask:0xf bank_mask:0xf
	v_fmac_f32_dpp v214, v104, v132 row_shr:1 row_mask:0xf bank_mask:0xf
	v_fmac_f32_dpp v215, v105, v133 row_shr:1 row_mask:0xf bank_mask:0xf
	v_fmac_f32_dpp v216, v106, v134 row_shr:1 row_mask:0xf bank_mask:0xf
	v_fmac_f32_dpp v217, v107, v135 row_shr:1 row_mask:0xf bank_mask:0xf
	v_fmac_f32_dpp v210, v108, v88 row_shr:2 row_mask:0xf bank_mask:0xf
	v_fmac_f32_dpp v211, v109, v89 row_shr:2 row_mask:0xf bank_mask:0xf
	v_fmac_f32_dpp v212, v110, v90 row_shr:2 row_mask:0xf bank_mask:0xf
	v_fmac_f32_dpp v213, v111, v91 row_shr:2 row_mask:0xf bank_mask:0xf
	v_fmac_f32_dpp v214, v104, v92 row_shr:2 row_mask:0xf bank_mask:0xf
	v_fmac_f32_dpp v215, v105, v93 row_shr:2 row_mask:0xf bank_mask:0xf
	v_fmac_f32_dpp v216, v106, v94 row_shr:2 row_mask:0xf bank_mask:0xf
	v_fmac_f32_dpp v217, v107, v95 row_shr:2 row_mask:0xf bank_mask:0xf
	v_fmac_f32_dpp v210, v124, v128 row_shl:15 row_mask:0xf bank_mask:0xf
	v_fmac_f32_dpp v211, v125, v129 row_shl:15 row_mask:0xf bank_mask:0xf
	v_fmac_f32_dpp v212, v126, v130 row_shl:15 row_mask:0xf bank_mask:0xf
	v_fmac_f32_dpp v213, v127, v131 row_shl:15 row_mask:0xf bank_mask:0xf
	v_fmac_f32_dpp v214, v120, v132 row_shl:15 row_mask:0xf bank_mask:0xf
	v_fmac_f32_dpp v215, v121, v133 row_shl:15 row_mask:0xf bank_mask:0xf
	v_fmac_f32_dpp v216, v122, v134 row_shl:15 row_mask:0xf bank_mask:0xf
	v_fmac_f32_dpp v217, v123, v135 row_shl:15 row_mask:0xf bank_mask:0xf
	v_fmac_f32_dpp v210, v124, v88 row_shl:14 row_mask:0xf bank_mask:0xf
	v_fmac_f32_dpp v211, v125, v89 row_shl:14 row_mask:0xf bank_mask:0xf
	v_fmac_f32_dpp v212, v126, v90 row_shl:14 row_mask:0xf bank_mask:0xf
	v_fmac_f32_dpp v213, v127, v91 row_shl:14 row_mask:0xf bank_mask:0xf
	v_fmac_f32_dpp v214, v120, v92 row_shl:14 row_mask:0xf bank_mask:0xf
	v_fmac_f32_dpp v215, v121, v93 row_shl:14 row_mask:0xf bank_mask:0xf
	v_fmac_f32_dpp v216, v122, v94 row_shl:14 row_mask:0xf bank_mask:0xf
	v_fmac_f32_dpp v217, v123, v95 row_shl:14 row_mask:0xf bank_mask:0xf
	v_exp_f32_e32 v218, v210
	v_exp_f32_e32 v219, v211
	v_exp_f32_e32 v220, v212
	v_exp_f32_e32 v221, v213
	v_exp_f32_e32 v222, v214
	v_exp_f32_e32 v223, v215
	v_exp_f32_e32 v224, v216
	v_exp_f32_e32 v225, v217
	v_add_f32_e32 v218, 1.0, v218
	v_add_f32_e32 v219, 1.0, v219
	v_add_f32_e32 v220, 1.0, v220
	v_add_f32_e32 v221, 1.0, v221
	v_add_f32_e32 v222, 1.0, v222
	v_add_f32_e32 v223, 1.0, v223
	v_add_f32_e32 v224, 1.0, v224
	v_add_f32_e32 v225, 1.0, v225
	v_rcp_f32_e32 v218, v218
	v_rcp_f32_e32 v219, v219
	v_rcp_f32_e32 v220, v220
	v_rcp_f32_e32 v221, v221
	v_rcp_f32_e32 v222, v222
	v_rcp_f32_e32 v223, v223
	v_rcp_f32_e32 v224, v224
	v_rcp_f32_e32 v225, v225
	v_mul_f32_e32 v100, v100, v204
	v_mul_f32_e32 v101, v101, v204
	v_mul_f32_e32 v102, v102, v204
	v_mul_f32_e32 v103, v103, v204
	v_mul_f32_e32 v96, v96, v204
	v_mul_f32_e32 v97, v97, v204
	v_mul_f32_e32 v98, v98, v204
	v_mul_f32_e32 v99, v99, v204
	v_mul_f32_e32 v210, v210, v218
	v_mul_f32_e32 v211, v211, v219
	v_mul_f32_e32 v212, v212, v220
	v_mul_f32_e32 v213, v213, v221
	v_mul_f32_e32 v214, v214, v222
	v_mul_f32_e32 v215, v215, v223
	v_mul_f32_e32 v216, v216, v224
	v_mul_f32_e32 v217, v217, v225
	v_mul_f32_e32 v100, v210, v100
	v_mul_f32_e32 v101, v211, v101
	v_mul_f32_e32 v102, v212, v102
	v_mul_f32_e32 v103, v213, v103
	v_mul_f32_e32 v96, v214, v96
	v_mul_f32_e32 v97, v215, v97
	v_mul_f32_e32 v98, v216, v98
	v_mul_f32_e32 v99, v217, v99
	v_cvt_pk_bf16_f32 v226, v100, v101
	v_cvt_pk_bf16_f32 v227, v102, v103
	v_cvt_pk_bf16_f32 v228, v96, v97
	v_cvt_pk_bf16_f32 v229, v98, v99
	v_add_u32_e32 v234, 0x2c000, v230
	global_store_dwordx4 v234, v[226:229], s[96:97] nt
	v_mul_f32_e32 v84, v84, v185
	v_mul_f32_e32 v85, v85, v185
	v_mul_f32_e32 v86, v86, v185
	v_mul_f32_e32 v87, v87, v185
	v_mul_f32_e32 v80, v80, v185
	v_mul_f32_e32 v81, v81, v185
	v_mul_f32_e32 v82, v82, v185
	v_mul_f32_e32 v83, v83, v185
	v_fma_f32 v210, v84, v136, v174
	v_fma_f32 v211, v85, v137, v175
	v_fma_f32 v212, v86, v138, v176
	v_fma_f32 v213, v87, v139, v177
	v_fma_f32 v214, v80, v140, v178
	v_fma_f32 v215, v81, v141, v179
	v_fma_f32 v216, v82, v142, v180
	v_fma_f32 v217, v83, v143, v181
	v_cvt_pk_bf16_f32 v236, v84, v85
	v_cvt_pk_bf16_f32 v237, v86, v87
	v_cvt_pk_bf16_f32 v238, v80, v81
	v_cvt_pk_bf16_f32 v239, v82, v83
	v_add_u32_e32 v235, 0xfffecc00, v233
	s_and_b64 exec, exec, s[10:11]
	global_store_dwordx4 v235, v[236:239], s[42:43]
	s_mov_b64 exec, s[24:25]
	v_fmac_f32_dpp v210, v84, v128 row_shr:1 row_mask:0xf bank_mask:0xf
	v_fmac_f32_dpp v211, v85, v129 row_shr:1 row_mask:0xf bank_mask:0xf
;     __device__ __forceinline__ void operator()(const Acc& acc, const Unit& u, int wr, int wc, int fr, int fq, LAS unsigned char* lds, f32x4 epar) const {
;     ...
;             for (int m = 0; m < 4; ++m) {
;                 const int r = u.pm * BM + ai * HALF + wr * 64 + m * 16 + fr;
;                 const float rs = __builtin_amdgcn_rsqf(sq[ai][m] * (1.0f / DM) + RMS_EPS);
;                 float X[NV], Y[NV], o[NV];
;                 if (MODE == 0) {
; #pragma unroll
;                     for (int n = 0; n < 2; ++n)
; #pragma unroll
;                         for (int j = 0; j < 4; ++j) { X[n * 4 + j] = acc[ai][0][m][n][j] * rs; Y[n * 4 + j] = acc[ai][1][m][n][j] * rs; }
;                 } else {
; #pragma unroll
;                     for (int j = 0; j < 4; ++j) { X[j] = (acc[ai][0][m][1][j] * rs) * (acc[ai][1][m][0][j] * rs); Y[j] = acc[ai][0][m][0][j] * rs; }
;                 }
; #pragma unroll
;                 for (int i = 0; i < NV; ++i) {
;                     const float a1 = dpp_rot<0x121>(X[i]), a2 = dpp_rot<0x122>(X[i]);
;                     const float q1 = fr >= 1 ? a1 : p1prev[i], q2 = fr >= 2 ? a2 : p2prev[i];
;                     p1prev[i] = a1; p2prev[i] = a2;
;                     const float cv = w2[i] * X[i] + w1[i] * q1 + w0[i] * q2 + bb[i];
;                     o[i] = MODE == 0 ? silu_f(cv) * Y[i] : cv * Y[i];
;                 }
;                 if (m == 0 && fr < 2) {
;                     bf16_t* hx = halo + ((size_t)strip * 6 + 2 + fr) * C + c0; bf16_t* hy = halo + ((size_t)strip * 6 + 4 + fr) * C + c0;
;                     u32x4 px, py; px.x = cvt_pk_bf16(X[0], X[1]); px.y = cvt_pk_bf16(X[2], X[3]); px.z = cvt_pk_bf16(X[4 % NV], X[5 % NV]); px.w = cvt_pk_bf16(X[6 % NV], X[7 % NV]);
;                     py.x = cvt_pk_bf16(Y[0], Y[1]); py.y = cvt_pk_bf16(Y[2], Y[3]); py.z = cvt_pk_bf16(Y[4 % NV], Y[5 % NV]); py.w = cvt_pk_bf16(Y[6 % NV], Y[7 % NV]);
;                     if (MODE == 0) { *(u32x4*)hx = px; *(u32x4*)hy = py; } else { u32x2 a; a.x = px.x; a.y = px.y; *(u32x2*)hx = a; u32x2 b; b.x = py.x; b.y = py.y; *(u32x2*)hy = b; }
;                 } else {
;                     if (MODE == 0) { u32x4 w; w.x = cvt_pk_bf16(o[0], o[1]); w.y = cvt_pk_bf16(o[2], o[3]); w.z = cvt_pk_bf16(o[4 % NV], o[5 % NV]); w.w = cvt_pk_bf16(o[6 % NV], o[7 % NV]);
	v_fmac_f32_dpp v212, v86, v130 row_shr:1 row_mask:0xf bank_mask:0xf
	v_fmac_f32_dpp v213, v87, v131 row_shr:1 row_mask:0xf bank_mask:0xf
	v_fmac_f32_dpp v214, v80, v132 row_shr:1 row_mask:0xf bank_mask:0xf
	v_fmac_f32_dpp v215, v81, v133 row_shr:1 row_mask:0xf bank_mask:0xf
	v_fmac_f32_dpp v216, v82, v134 row_shr:1 row_mask:0xf bank_mask:0xf
	v_fmac_f32_dpp v217, v83, v135 row_shr:1 row_mask:0xf bank_mask:0xf
	v_fmac_f32_dpp v210, v84, v88 row_shr:2 row_mask:0xf bank_mask:0xf
	v_fmac_f32_dpp v211, v85, v89 row_shr:2 row_mask:0xf bank_mask:0xf
	v_fmac_f32_dpp v212, v86, v90 row_shr:2 row_mask:0xf bank_mask:0xf
	v_fmac_f32_dpp v213, v87, v91 row_shr:2 row_mask:0xf bank_mask:0xf
	v_fmac_f32_dpp v214, v80, v92 row_shr:2 row_mask:0xf bank_mask:0xf
	v_fmac_f32_dpp v215, v81, v93 row_shr:2 row_mask:0xf bank_mask:0xf
	v_fmac_f32_dpp v216, v82, v94 row_shr:2 row_mask:0xf bank_mask:0xf
	v_fmac_f32_dpp v217, v83, v95 row_shr:2 row_mask:0xf bank_mask:0xf
	v_fmac_f32_dpp v210, v108, v128 row_shl:15 row_mask:0xf bank_mask:0xf
	v_fmac_f32_dpp v211, v109, v129 row_shl:15 row_mask:0xf bank_mask:0xf
	v_fmac_f32_dpp v212, v110, v130 row_shl:15 row_mask:0xf bank_mask:0xf
	v_fmac_f32_dpp v213, v111, v131 row_shl:15 row_mask:0xf bank_mask:0xf
	v_fmac_f32_dpp v214, v104, v132 row_shl:15 row_mask:0xf bank_mask:0xf
	v_fmac_f32_dpp v215, v105, v133 row_shl:15 row_mask:0xf bank_mask:0xf
	v_fmac_f32_dpp v216, v106, v134 row_shl:15 row_mask:0xf bank_mask:0xf
	v_fmac_f32_dpp v217, v107, v135 row_shl:15 row_mask:0xf bank_mask:0xf
	v_fmac_f32_dpp v210, v108, v88 row_shl:14 row_mask:0xf bank_mask:0xf
	v_fmac_f32_dpp v211, v109, v89 row_shl:14 row_mask:0xf bank_mask:0xf
	v_fmac_f32_dpp v212, v110, v90 row_shl:14 row_mask:0xf bank_mask:0xf
	v_fmac_f32_dpp v213, v111, v91 row_shl:14 row_mask:0xf bank_mask:0xf
	v_fmac_f32_dpp v214, v104, v92 row_shl:14 row_mask:0xf bank_mask:0xf
	v_fmac_f32_dpp v215, v105, v93 row_shl:14 row_mask:0xf bank_mask:0xf
	v_fmac_f32_dpp v216, v106, v94 row_shl:14 row_mask:0xf bank_mask:0xf
	v_fmac_f32_dpp v217, v107, v95 row_shl:14 row_mask:0xf bank_mask:0xf
	v_exp_f32_e32 v218, v210
	v_exp_f32_e32 v219, v211
	v_exp_f32_e32 v220, v212
	v_exp_f32_e32 v221, v213
	v_exp_f32_e32 v222, v214
	v_exp_f32_e32 v223, v215
	v_exp_f32_e32 v224, v216
	v_exp_f32_e32 v225, v217
	v_add_f32_e32 v218, 1.0, v218
	v_add_f32_e32 v219, 1.0, v219
	v_add_f32_e32 v220, 1.0, v220
	v_add_f32_e32 v221, 1.0, v221
	v_add_f32_e32 v222, 1.0, v222
	v_add_f32_e32 v223, 1.0, v223
	v_add_f32_e32 v224, 1.0, v224
	v_add_f32_e32 v225, 1.0, v225
	v_rcp_f32_e32 v218, v218
	v_rcp_f32_e32 v219, v219
	v_rcp_f32_e32 v220, v220
	v_rcp_f32_e32 v221, v221
	v_rcp_f32_e32 v222, v222
	v_rcp_f32_e32 v223, v223
	v_rcp_f32_e32 v224, v224
	v_rcp_f32_e32 v225, v225
	v_mul_f32_e32 v68, v68, v205
	v_mul_f32_e32 v69, v69, v205
	v_mul_f32_e32 v70, v70, v205
	v_mul_f32_e32 v71, v71, v205
	v_mul_f32_e32 v64, v64, v205
	v_mul_f32_e32 v65, v65, v205
	v_mul_f32_e32 v66, v66, v205
	v_mul_f32_e32 v67, v67, v205
	v_mul_f32_e32 v210, v210, v218
	v_mul_f32_e32 v211, v211, v219
	v_mul_f32_e32 v212, v212, v220
	v_mul_f32_e32 v213, v213, v221
	v_mul_f32_e32 v214, v214, v222
	v_mul_f32_e32 v215, v215, v223
	v_mul_f32_e32 v216, v216, v224
	v_mul_f32_e32 v217, v217, v225
	v_mul_f32_e32 v68, v210, v68
	v_mul_f32_e32 v69, v211, v69
	v_mul_f32_e32 v70, v212, v70
	v_mul_f32_e32 v71, v213, v71
	v_mul_f32_e32 v64, v214, v64
	v_mul_f32_e32 v65, v215, v65
	v_mul_f32_e32 v66, v216, v66
	v_mul_f32_e32 v67, v217, v67
	v_cvt_pk_bf16_f32 v226, v68, v69
	v_cvt_pk_bf16_f32 v227, v70, v71
	v_cvt_pk_bf16_f32 v228, v64, v65
	v_cvt_pk_bf16_f32 v229, v66, v67
	v_add_u32_e32 v234, 0x42000, v230
	global_store_dwordx4 v234, v[226:229], s[96:97] nt
	v_mul_f32_e32 v60, v60, v76
	v_mul_f32_e32 v61, v61, v76
	v_mul_f32_e32 v62, v62, v76
	v_mul_f32_e32 v63, v63, v76
	v_mul_f32_e32 v52, v52, v76
	v_mul_f32_e32 v53, v53, v76
	v_mul_f32_e32 v54, v54, v76
	v_mul_f32_e32 v55, v55, v76
	v_fma_f32 v210, v60, v136, v174
	v_fma_f32 v211, v61, v137, v175
	v_fma_f32 v212, v62, v138, v176
	v_fma_f32 v213, v63, v139, v177
	v_fma_f32 v214, v52, v140, v178
	v_fma_f32 v215, v53, v141, v179
	v_fma_f32 v216, v54, v142, v180
	v_fma_f32 v217, v55, v143, v181
	v_mul_f32_e32 v218, v56, v76
	v_mul_f32_e32 v219, v57, v76
	v_mul_f32_e32 v220, v58, v76
	v_mul_f32_e32 v221, v59, v76
	v_mul_f32_e32 v222, v48, v76
	v_mul_f32_e32 v223, v49, v76
	v_mul_f32_e32 v224, v50, v76
	v_mul_f32_e32 v225, v51, v76
	v_cvt_pk_bf16_f32 v236, v60, v61
	v_cvt_pk_bf16_f32 v237, v62, v63
	v_cvt_pk_bf16_f32 v238, v52, v53
	v_cvt_pk_bf16_f32 v239, v54, v55
	v_cvt_pk_bf16_f32 v240, v218, v219
	v_cvt_pk_bf16_f32 v241, v220, v221
	v_cvt_pk_bf16_f32 v242, v222, v223
	v_cvt_pk_bf16_f32 v243, v224, v225
	v_add_u32_e32 v234, 0x13400, v233
	v_add_u32_e32 v235, 0x16000, v233
	s_andn2_b64 exec, exec, s[8:9]
	global_store_dwordx4 v234, v[236:239], s[42:43]
	global_store_dwordx4 v235, v[240:243], s[42:43]
	s_mov_b64 exec, s[24:25]
	v_fmac_f32_dpp v210, v60, v128 row_shr:1 row_mask:0xf bank_mask:0xf
	v_fmac_f32_dpp v211, v61, v129 row_shr:1 row_mask:0xf bank_mask:0xf
	v_fmac_f32_dpp v212, v62, v130 row_shr:1 row_mask:0xf bank_mask:0xf
	v_fmac_f32_dpp v213, v63, v131 row_shr:1 row_mask:0xf bank_mask:0xf
	v_fmac_f32_dpp v214, v52, v132 row_shr:1 row_mask:0xf bank_mask:0xf
	v_fmac_f32_dpp v215, v53, v133 row_shr:1 row_mask:0xf bank_mask:0xf
	v_fmac_f32_dpp v216, v54, v134 row_shr:1 row_mask:0xf bank_mask:0xf
	v_fmac_f32_dpp v217, v55, v135 row_shr:1 row_mask:0xf bank_mask:0xf
	v_fmac_f32_dpp v210, v60, v88 row_shr:2 row_mask:0xf bank_mask:0xf
	v_fmac_f32_dpp v211, v61, v89 row_shr:2 row_mask:0xf bank_mask:0xf
;     __device__ __forceinline__ void operator()(const Acc& acc, const Unit& u, int wr, int wc, int fr, int fq, LAS unsigned char* lds, f32x4 epar) const {
;     ...
;             for (int m = 0; m < 4; ++m) {
;                 const int r = u.pm * BM + ai * HALF + wr * 64 + m * 16 + fr;
;                 const float rs = __builtin_amdgcn_rsqf(sq[ai][m] * (1.0f / DM) + RMS_EPS);
;                 float X[NV], Y[NV], o[NV];
;                 if (MODE == 0) {
; #pragma unroll
;                     for (int n = 0; n < 2; ++n)
; #pragma unroll
;                         for (int j = 0; j < 4; ++j) { X[n * 4 + j] = acc[ai][0][m][n][j] * rs; Y[n * 4 + j] = acc[ai][1][m][n][j] * rs; }
;                 } else {
; #pragma unroll
;                     for (int j = 0; j < 4; ++j) { X[j] = (acc[ai][0][m][1][j] * rs) * (acc[ai][1][m][0][j] * rs); Y[j] = acc[ai][0][m][0][j] * rs; }
;                 }
; #pragma unroll
;                 for (int i = 0; i < NV; ++i) {
;                     const float a1 = dpp_rot<0x121>(X[i]), a2 = dpp_rot<0x122>(X[i]);
;                     const float q1 = fr >= 1 ? a1 : p1prev[i], q2 = fr >= 2 ? a2 : p2prev[i];
;                     p1prev[i] = a1; p2prev[i] = a2;
;                     const float cv = w2[i] * X[i] + w1[i] * q1 + w0[i] * q2 + bb[i];
;                     o[i] = MODE == 0 ? silu_f(cv) * Y[i] : cv * Y[i];
;                 }
;                 if (m == 0 && fr < 2) {
;                     bf16_t* hx = halo + ((size_t)strip * 6 + 2 + fr) * C + c0; bf16_t* hy = halo + ((size_t)strip * 6 + 4 + fr) * C + c0;
;                     u32x4 px, py; px.x = cvt_pk_bf16(X[0], X[1]); px.y = cvt_pk_bf16(X[2], X[3]); px.z = cvt_pk_bf16(X[4 % NV], X[5 % NV]); px.w = cvt_pk_bf16(X[6 % NV], X[7 % NV]);
;                     py.x = cvt_pk_bf16(Y[0], Y[1]); py.y = cvt_pk_bf16(Y[2], Y[3]); py.z = cvt_pk_bf16(Y[4 % NV], Y[5 % NV]); py.w = cvt_pk_bf16(Y[6 % NV], Y[7 % NV]);
;                     if (MODE == 0) { *(u32x4*)hx = px; *(u32x4*)hy = py; } else { u32x2 a; a.x = px.x; a.y = px.y; *(u32x2*)hx = a; u32x2 b; b.x = py.x; b.y = py.y; *(u32x2*)hy = b; }
;                 } else {
;                     if (MODE == 0) { u32x4 w; w.x = cvt_pk_bf16(o[0], o[1]); w.y = cvt_pk_bf16(o[2], o[3]); w.z = cvt_pk_bf16(o[4 % NV], o[5 % NV]); w.w = cvt_pk_bf16(o[6 % NV], o[7 % NV]);
	v_fmac_f32_dpp v212, v62, v90 row_shr:2 row_mask:0xf bank_mask:0xf
	v_fmac_f32_dpp v213, v63, v91 row_shr:2 row_mask:0xf bank_mask:0xf
	v_fmac_f32_dpp v214, v52, v92 row_shr:2 row_mask:0xf bank_mask:0xf
	v_fmac_f32_dpp v215, v53, v93 row_shr:2 row_mask:0xf bank_mask:0xf
	v_fmac_f32_dpp v216, v54, v94 row_shr:2 row_mask:0xf bank_mask:0xf
	v_fmac_f32_dpp v217, v55, v95 row_shr:2 row_mask:0xf bank_mask:0xf
	v_exp_f32_e32 v218, v210
	v_exp_f32_e32 v219, v211
	v_exp_f32_e32 v220, v212
	v_exp_f32_e32 v221, v213
	v_exp_f32_e32 v222, v214
	v_exp_f32_e32 v223, v215
	v_exp_f32_e32 v224, v216
	v_exp_f32_e32 v225, v217
	v_add_f32_e32 v218, 1.0, v218
	v_add_f32_e32 v219, 1.0, v219
	v_add_f32_e32 v220, 1.0, v220
	v_add_f32_e32 v221, 1.0, v221
	v_add_f32_e32 v222, 1.0, v222
	v_add_f32_e32 v223, 1.0, v223
	v_add_f32_e32 v224, 1.0, v224
	v_add_f32_e32 v225, 1.0, v225
	v_rcp_f32_e32 v218, v218
	v_rcp_f32_e32 v219, v219
	v_rcp_f32_e32 v220, v220
	v_rcp_f32_e32 v221, v221
	v_rcp_f32_e32 v222, v222
	v_rcp_f32_e32 v223, v223
	v_rcp_f32_e32 v224, v224
	v_rcp_f32_e32 v225, v225
	v_mul_f32_e32 v56, v56, v206
	v_mul_f32_e32 v57, v57, v206
	v_mul_f32_e32 v58, v58, v206
	v_mul_f32_e32 v59, v59, v206
	v_mul_f32_e32 v48, v48, v206
	v_mul_f32_e32 v49, v49, v206
	v_mul_f32_e32 v50, v50, v206
	v_mul_f32_e32 v51, v51, v206
	v_mul_f32_e32 v210, v210, v218
	v_mul_f32_e32 v211, v211, v219
	v_mul_f32_e32 v212, v212, v220
	v_mul_f32_e32 v213, v213, v221
	v_mul_f32_e32 v214, v214, v222
	v_mul_f32_e32 v215, v215, v223
	v_mul_f32_e32 v216, v216, v224
	v_mul_f32_e32 v217, v217, v225
	v_mul_f32_e32 v56, v210, v56
	v_mul_f32_e32 v57, v211, v57
	v_mul_f32_e32 v58, v212, v58
	v_mul_f32_e32 v59, v213, v59
	v_mul_f32_e32 v48, v214, v48
	v_mul_f32_e32 v49, v215, v49
	v_mul_f32_e32 v50, v216, v50
	v_mul_f32_e32 v51, v217, v51
	v_cvt_pk_bf16_f32 v226, v56, v57
	v_cvt_pk_bf16_f32 v227, v58, v59
	v_cvt_pk_bf16_f32 v228, v48, v49
	v_cvt_pk_bf16_f32 v229, v50, v51
	v_add_u32_e32 v234, 0xb0000, v230
	s_and_b64 exec, exec, s[8:9]
	global_store_dwordx4 v234, v[226:229], s[96:97] nt
	s_mov_b64 exec, s[24:25]
	v_mul_f32_e32 v44, v44, v77
	v_mul_f32_e32 v45, v45, v77
	v_mul_f32_e32 v46, v46, v77
	v_mul_f32_e32 v47, v47, v77
	v_mul_f32_e32 v40, v40, v77
	v_mul_f32_e32 v41, v41, v77
	v_mul_f32_e32 v42, v42, v77
	v_mul_f32_e32 v43, v43, v77
	v_fma_f32 v210, v44, v136, v174
	v_fma_f32 v211, v45, v137, v175
	v_fma_f32 v212, v46, v138, v176
	v_fma_f32 v213, v47, v139, v177
	v_fma_f32 v214, v40, v140, v178
	v_fma_f32 v215, v41, v141, v179
	v_fma_f32 v216, v42, v142, v180
	v_fma_f32 v217, v43, v143, v181
	v_fmac_f32_dpp v210, v44, v128 row_shr:1 row_mask:0xf bank_mask:0xf
	v_fmac_f32_dpp v211, v45, v129 row_shr:1 row_mask:0xf bank_mask:0xf
	v_fmac_f32_dpp v212, v46, v130 row_shr:1 row_mask:0xf bank_mask:0xf
	v_fmac_f32_dpp v213, v47, v131 row_shr:1 row_mask:0xf bank_mask:0xf
	v_fmac_f32_dpp v214, v40, v132 row_shr:1 row_mask:0xf bank_mask:0xf
	v_fmac_f32_dpp v215, v41, v133 row_shr:1 row_mask:0xf bank_mask:0xf
	v_fmac_f32_dpp v216, v42, v134 row_shr:1 row_mask:0xf bank_mask:0xf
	v_fmac_f32_dpp v217, v43, v135 row_shr:1 row_mask:0xf bank_mask:0xf
	v_fmac_f32_dpp v210, v44, v88 row_shr:2 row_mask:0xf bank_mask:0xf
	v_fmac_f32_dpp v211, v45, v89 row_shr:2 row_mask:0xf bank_mask:0xf
	v_fmac_f32_dpp v212, v46, v90 row_shr:2 row_mask:0xf bank_mask:0xf
	v_fmac_f32_dpp v213, v47, v91 row_shr:2 row_mask:0xf bank_mask:0xf
	v_fmac_f32_dpp v214, v40, v92 row_shr:2 row_mask:0xf bank_mask:0xf
	v_fmac_f32_dpp v215, v41, v93 row_shr:2 row_mask:0xf bank_mask:0xf
	v_fmac_f32_dpp v216, v42, v94 row_shr:2 row_mask:0xf bank_mask:0xf
	v_fmac_f32_dpp v217, v43, v95 row_shr:2 row_mask:0xf bank_mask:0xf
	v_fmac_f32_dpp v210, v60, v128 row_shl:15 row_mask:0xf bank_mask:0xf
	v_fmac_f32_dpp v211, v61, v129 row_shl:15 row_mask:0xf bank_mask:0xf
	v_fmac_f32_dpp v212, v62, v130 row_shl:15 row_mask:0xf bank_mask:0xf
	v_fmac_f32_dpp v213, v63, v131 row_shl:15 row_mask:0xf bank_mask:0xf
	v_fmac_f32_dpp v214, v52, v132 row_shl:15 row_mask:0xf bank_mask:0xf
	v_fmac_f32_dpp v215, v53, v133 row_shl:15 row_mask:0xf bank_mask:0xf
	v_fmac_f32_dpp v216, v54, v134 row_shl:15 row_mask:0xf bank_mask:0xf
	v_fmac_f32_dpp v217, v55, v135 row_shl:15 row_mask:0xf bank_mask:0xf
	v_fmac_f32_dpp v210, v60, v88 row_shl:14 row_mask:0xf bank_mask:0xf
	v_fmac_f32_dpp v211, v61, v89 row_shl:14 row_mask:0xf bank_mask:0xf
	v_fmac_f32_dpp v212, v62, v90 row_shl:14 row_mask:0xf bank_mask:0xf
	v_fmac_f32_dpp v213, v63, v91 row_shl:14 row_mask:0xf bank_mask:0xf
	v_fmac_f32_dpp v214, v52, v92 row_shl:14 row_mask:0xf bank_mask:0xf
	v_fmac_f32_dpp v215, v53, v93 row_shl:14 row_mask:0xf bank_mask:0xf
	v_fmac_f32_dpp v216, v54, v94 row_shl:14 row_mask:0xf bank_mask:0xf
	v_fmac_f32_dpp v217, v55, v95 row_shl:14 row_mask:0xf bank_mask:0xf
	v_exp_f32_e32 v218, v210
	v_exp_f32_e32 v219, v211
	v_exp_f32_e32 v220, v212
	v_exp_f32_e32 v221, v213
	v_exp_f32_e32 v222, v214
	v_exp_f32_e32 v223, v215
	v_exp_f32_e32 v224, v216
	v_exp_f32_e32 v225, v217
	v_add_f32_e32 v218, 1.0, v218
	v_add_f32_e32 v219, 1.0, v219
	v_add_f32_e32 v220, 1.0, v220
	v_add_f32_e32 v221, 1.0, v221
	v_add_f32_e32 v222, 1.0, v222
	v_add_f32_e32 v223, 1.0, v223
	v_add_f32_e32 v224, 1.0, v224
	v_add_f32_e32 v225, 1.0, v225
	v_rcp_f32_e32 v218, v218
	v_rcp_f32_e32 v219, v219
	v_rcp_f32_e32 v220, v220
	v_rcp_f32_e32 v221, v221
	v_rcp_f32_e32 v222, v222
	v_rcp_f32_e32 v223, v223
	v_rcp_f32_e32 v224, v224
	v_rcp_f32_e32 v225, v225
	v_mul_f32_e32 v36, v36, v207
	v_mul_f32_e32 v37, v37, v207
	v_mul_f32_e32 v38, v38, v207
	v_mul_f32_e32 v39, v39, v207
	v_mul_f32_e32 v32, v32, v207
	v_mul_f32_e32 v33, v33, v207
;     __device__ __forceinline__ void operator()(const Acc& acc, const Unit& u, int wr, int wc, int fr, int fq, LAS unsigned char* lds, f32x4 epar) const {
;     ...
;             for (int m = 0; m < 4; ++m) {
;                 const int r = u.pm * BM + ai * HALF + wr * 64 + m * 16 + fr;
;                 const float rs = __builtin_amdgcn_rsqf(sq[ai][m] * (1.0f / DM) + RMS_EPS);
;                 float X[NV], Y[NV], o[NV];
;                 if (MODE == 0) {
; #pragma unroll
;                     for (int n = 0; n < 2; ++n)
; #pragma unroll
;                         for (int j = 0; j < 4; ++j) { X[n * 4 + j] = acc[ai][0][m][n][j] * rs; Y[n * 4 + j] = acc[ai][1][m][n][j] * rs; }
;                 } else {
; #pragma unroll
;                     for (int j = 0; j < 4; ++j) { X[j] = (acc[ai][0][m][1][j] * rs) * (acc[ai][1][m][0][j] * rs); Y[j] = acc[ai][0][m][0][j] * rs; }
;                 }
; #pragma unroll
;                 for (int i = 0; i < NV; ++i) {
;                     const float a1 = dpp_rot<0x121>(X[i]), a2 = dpp_rot<0x122>(X[i]);
;                     const float q1 = fr >= 1 ? a1 : p1prev[i], q2 = fr >= 2 ? a2 : p2prev[i];
;                     p1prev[i] = a1; p2prev[i] = a2;
;                     const float cv = w2[i] * X[i] + w1[i] * q1 + w0[i] * q2 + bb[i];
;                     o[i] = MODE == 0 ? silu_f(cv) * Y[i] : cv * Y[i];
;                 }
;                 if (m == 0 && fr < 2) {
;                     bf16_t* hx = halo + ((size_t)strip * 6 + 2 + fr) * C + c0; bf16_t* hy = halo + ((size_t)strip * 6 + 4 + fr) * C + c0;
;                     u32x4 px, py; px.x = cvt_pk_bf16(X[0], X[1]); px.y = cvt_pk_bf16(X[2], X[3]); px.z = cvt_pk_bf16(X[4 % NV], X[5 % NV]); px.w = cvt_pk_bf16(X[6 % NV], X[7 % NV]);
;                     py.x = cvt_pk_bf16(Y[0], Y[1]); py.y = cvt_pk_bf16(Y[2], Y[3]); py.z = cvt_pk_bf16(Y[4 % NV], Y[5 % NV]); py.w = cvt_pk_bf16(Y[6 % NV], Y[7 % NV]);
;                     if (MODE == 0) { *(u32x4*)hx = px; *(u32x4*)hy = py; } else { u32x2 a; a.x = px.x; a.y = px.y; *(u32x2*)hx = a; u32x2 b; b.x = py.x; b.y = py.y; *(u32x2*)hy = b; }
;                 } else {
;                     if (MODE == 0) { u32x4 w; w.x = cvt_pk_bf16(o[0], o[1]); w.y = cvt_pk_bf16(o[2], o[3]); w.z = cvt_pk_bf16(o[4 % NV], o[5 % NV]); w.w = cvt_pk_bf16(o[6 % NV], o[7 % NV]);
	v_mul_f32_e32 v34, v34, v207
	v_mul_f32_e32 v35, v35, v207
	v_mul_f32_e32 v210, v210, v218
	v_mul_f32_e32 v211, v211, v219
	v_mul_f32_e32 v212, v212, v220
	v_mul_f32_e32 v213, v213, v221
	v_mul_f32_e32 v214, v214, v222
	v_mul_f32_e32 v215, v215, v223
	v_mul_f32_e32 v216, v216, v224
	v_mul_f32_e32 v217, v217, v225
	v_mul_f32_e32 v36, v210, v36
	v_mul_f32_e32 v37, v211, v37
	v_mul_f32_e32 v38, v212, v38
	v_mul_f32_e32 v39, v213, v39
	v_mul_f32_e32 v32, v214, v32
	v_mul_f32_e32 v33, v215, v33
	v_mul_f32_e32 v34, v216, v34
	v_mul_f32_e32 v35, v217, v35
	v_cvt_pk_bf16_f32 v226, v36, v37
	v_cvt_pk_bf16_f32 v227, v38, v39
	v_cvt_pk_bf16_f32 v228, v32, v33
	v_cvt_pk_bf16_f32 v229, v34, v35
	v_add_u32_e32 v234, 0xc6000, v230
	global_store_dwordx4 v234, v[226:229], s[96:97] nt
	v_mul_f32_e32 v28, v28, v78
	v_mul_f32_e32 v29, v29, v78
	v_mul_f32_e32 v30, v30, v78
	v_mul_f32_e32 v31, v31, v78
	v_mul_f32_e32 v24, v24, v78
	v_mul_f32_e32 v25, v25, v78
	v_mul_f32_e32 v26, v26, v78
	v_mul_f32_e32 v27, v27, v78
	v_fma_f32 v210, v28, v136, v174
	v_fma_f32 v211, v29, v137, v175
	v_fma_f32 v212, v30, v138, v176
	v_fma_f32 v213, v31, v139, v177
	v_fma_f32 v214, v24, v140, v178
	v_fma_f32 v215, v25, v141, v179
	v_fma_f32 v216, v26, v142, v180
	v_fma_f32 v217, v27, v143, v181
	v_fmac_f32_dpp v210, v28, v128 row_shr:1 row_mask:0xf bank_mask:0xf
	v_fmac_f32_dpp v211, v29, v129 row_shr:1 row_mask:0xf bank_mask:0xf
	v_fmac_f32_dpp v212, v30, v130 row_shr:1 row_mask:0xf bank_mask:0xf
	v_fmac_f32_dpp v213, v31, v131 row_shr:1 row_mask:0xf bank_mask:0xf
	v_fmac_f32_dpp v214, v24, v132 row_shr:1 row_mask:0xf bank_mask:0xf
	v_fmac_f32_dpp v215, v25, v133 row_shr:1 row_mask:0xf bank_mask:0xf
	v_fmac_f32_dpp v216, v26, v134 row_shr:1 row_mask:0xf bank_mask:0xf
	v_fmac_f32_dpp v217, v27, v135 row_shr:1 row_mask:0xf bank_mask:0xf
	v_fmac_f32_dpp v210, v28, v88 row_shr:2 row_mask:0xf bank_mask:0xf
	v_fmac_f32_dpp v211, v29, v89 row_shr:2 row_mask:0xf bank_mask:0xf
	v_fmac_f32_dpp v212, v30, v90 row_shr:2 row_mask:0xf bank_mask:0xf
	v_fmac_f32_dpp v213, v31, v91 row_shr:2 row_mask:0xf bank_mask:0xf
	v_fmac_f32_dpp v214, v24, v92 row_shr:2 row_mask:0xf bank_mask:0xf
	v_fmac_f32_dpp v215, v25, v93 row_shr:2 row_mask:0xf bank_mask:0xf
	v_fmac_f32_dpp v216, v26, v94 row_shr:2 row_mask:0xf bank_mask:0xf
	v_fmac_f32_dpp v217, v27, v95 row_shr:2 row_mask:0xf bank_mask:0xf
	v_fmac_f32_dpp v210, v44, v128 row_shl:15 row_mask:0xf bank_mask:0xf
	v_fmac_f32_dpp v211, v45, v129 row_shl:15 row_mask:0xf bank_mask:0xf
	v_fmac_f32_dpp v212, v46, v130 row_shl:15 row_mask:0xf bank_mask:0xf
	v_fmac_f32_dpp v213, v47, v131 row_shl:15 row_mask:0xf bank_mask:0xf
	v_fmac_f32_dpp v214, v40, v132 row_shl:15 row_mask:0xf bank_mask:0xf
	v_fmac_f32_dpp v215, v41, v133 row_shl:15 row_mask:0xf bank_mask:0xf
	v_fmac_f32_dpp v216, v42, v134 row_shl:15 row_mask:0xf bank_mask:0xf
	v_fmac_f32_dpp v217, v43, v135 row_shl:15 row_mask:0xf bank_mask:0xf
	v_fmac_f32_dpp v210, v44, v88 row_shl:14 row_mask:0xf bank_mask:0xf
	v_fmac_f32_dpp v211, v45, v89 row_shl:14 row_mask:0xf bank_mask:0xf
	v_fmac_f32_dpp v212, v46, v90 row_shl:14 row_mask:0xf bank_mask:0xf
	v_fmac_f32_dpp v213, v47, v91 row_shl:14 row_mask:0xf bank_mask:0xf
	v_fmac_f32_dpp v214, v40, v92 row_shl:14 row_mask:0xf bank_mask:0xf
	v_fmac_f32_dpp v215, v41, v93 row_shl:14 row_mask:0xf bank_mask:0xf
	v_fmac_f32_dpp v216, v42, v94 row_shl:14 row_mask:0xf bank_mask:0xf
	v_fmac_f32_dpp v217, v43, v95 row_shl:14 row_mask:0xf bank_mask:0xf
	v_exp_f32_e32 v218, v210
	v_exp_f32_e32 v219, v211
	v_exp_f32_e32 v220, v212
	v_exp_f32_e32 v221, v213
	v_exp_f32_e32 v222, v214
	v_exp_f32_e32 v223, v215
	v_exp_f32_e32 v224, v216
	v_exp_f32_e32 v225, v217
	v_add_f32_e32 v218, 1.0, v218
	v_add_f32_e32 v219, 1.0, v219
	v_add_f32_e32 v220, 1.0, v220
	v_add_f32_e32 v221, 1.0, v221
	v_add_f32_e32 v222, 1.0, v222
	v_add_f32_e32 v223, 1.0, v223
	v_add_f32_e32 v224, 1.0, v224
	v_add_f32_e32 v225, 1.0, v225
	v_rcp_f32_e32 v218, v218
	v_rcp_f32_e32 v219, v219
	v_rcp_f32_e32 v220, v220
	v_rcp_f32_e32 v221, v221
	v_rcp_f32_e32 v222, v222
	v_rcp_f32_e32 v223, v223
	v_rcp_f32_e32 v224, v224
	v_rcp_f32_e32 v225, v225
	v_mul_f32_e32 v20, v20, v208
	v_mul_f32_e32 v21, v21, v208
	v_mul_f32_e32 v22, v22, v208
	v_mul_f32_e32 v23, v23, v208
	v_mul_f32_e32 v16, v16, v208
	v_mul_f32_e32 v17, v17, v208
	v_mul_f32_e32 v18, v18, v208
	v_mul_f32_e32 v19, v19, v208
	v_mul_f32_e32 v210, v210, v218
	v_mul_f32_e32 v211, v211, v219
	v_mul_f32_e32 v212, v212, v220
	v_mul_f32_e32 v213, v213, v221
	v_mul_f32_e32 v214, v214, v222
	v_mul_f32_e32 v215, v215, v223
	v_mul_f32_e32 v216, v216, v224
	v_mul_f32_e32 v217, v217, v225
	v_mul_f32_e32 v20, v210, v20
	v_mul_f32_e32 v21, v211, v21
	v_mul_f32_e32 v22, v212, v22
	v_mul_f32_e32 v23, v213, v23
	v_mul_f32_e32 v16, v214, v16
	v_mul_f32_e32 v17, v215, v17
;     __device__ __forceinline__ void operator()(const Acc& acc, const Unit& u, int wr, int wc, int fr, int fq, LAS unsigned char* lds, f32x4 epar) const {
;     ...
;             for (int m = 0; m < 4; ++m) {
;                 const int r = u.pm * BM + ai * HALF + wr * 64 + m * 16 + fr;
;                 const float rs = __builtin_amdgcn_rsqf(sq[ai][m] * (1.0f / DM) + RMS_EPS);
;                 float X[NV], Y[NV], o[NV];
;                 if (MODE == 0) {
; #pragma unroll
;                     for (int n = 0; n < 2; ++n)
; #pragma unroll
;                         for (int j = 0; j < 4; ++j) { X[n * 4 + j] = acc[ai][0][m][n][j] * rs; Y[n * 4 + j] = acc[ai][1][m][n][j] * rs; }
;                 } else {
; #pragma unroll
;                     for (int j = 0; j < 4; ++j) { X[j] = (acc[ai][0][m][1][j] * rs) * (acc[ai][1][m][0][j] * rs); Y[j] = acc[ai][0][m][0][j] * rs; }
;                 }
; #pragma unroll
;                 for (int i = 0; i < NV; ++i) {
;                     const float a1 = dpp_rot<0x121>(X[i]), a2 = dpp_rot<0x122>(X[i]);
;                     const float q1 = fr >= 1 ? a1 : p1prev[i], q2 = fr >= 2 ? a2 : p2prev[i];
;                     p1prev[i] = a1; p2prev[i] = a2;
;                     const float cv = w2[i] * X[i] + w1[i] * q1 + w0[i] * q2 + bb[i];
;                     o[i] = MODE == 0 ? silu_f(cv) * Y[i] : cv * Y[i];
;                 }
;                 if (m == 0 && fr < 2) {
;                     bf16_t* hx = halo + ((size_t)strip * 6 + 2 + fr) * C + c0; bf16_t* hy = halo + ((size_t)strip * 6 + 4 + fr) * C + c0;
;                     u32x4 px, py; px.x = cvt_pk_bf16(X[0], X[1]); px.y = cvt_pk_bf16(X[2], X[3]); px.z = cvt_pk_bf16(X[4 % NV], X[5 % NV]); px.w = cvt_pk_bf16(X[6 % NV], X[7 % NV]);
;                     py.x = cvt_pk_bf16(Y[0], Y[1]); py.y = cvt_pk_bf16(Y[2], Y[3]); py.z = cvt_pk_bf16(Y[4 % NV], Y[5 % NV]); py.w = cvt_pk_bf16(Y[6 % NV], Y[7 % NV]);
;                     if (MODE == 0) { *(u32x4*)hx = px; *(u32x4*)hy = py; } else { u32x2 a; a.x = px.x; a.y = px.y; *(u32x2*)hx = a; u32x2 b; b.x = py.x; b.y = py.y; *(u32x2*)hy = b; }
;                 } else {
;                     if (MODE == 0) { u32x4 w; w.x = cvt_pk_bf16(o[0], o[1]); w.y = cvt_pk_bf16(o[2], o[3]); w.z = cvt_pk_bf16(o[4 % NV], o[5 % NV]); w.w = cvt_pk_bf16(o[6 % NV], o[7 % NV]);
	v_mul_f32_e32 v18, v216, v18
	v_mul_f32_e32 v19, v217, v19
	v_cvt_pk_bf16_f32 v226, v20, v21
	v_cvt_pk_bf16_f32 v227, v22, v23
	v_cvt_pk_bf16_f32 v228, v16, v17
	v_cvt_pk_bf16_f32 v229, v18, v19
	v_add_u32_e32 v234, 0xdc000, v230
	global_store_dwordx4 v234, v[226:229], s[96:97] nt
	v_mul_f32_e32 v12, v12, v79
	v_mul_f32_e32 v13, v13, v79
	v_mul_f32_e32 v14, v14, v79
	v_mul_f32_e32 v15, v15, v79
	v_mul_f32_e32 v8, v8, v79
	v_mul_f32_e32 v9, v9, v79
	v_mul_f32_e32 v10, v10, v79
	v_mul_f32_e32 v11, v11, v79
	v_fma_f32 v210, v12, v136, v174
	v_fma_f32 v211, v13, v137, v175
	v_fma_f32 v212, v14, v138, v176
	v_fma_f32 v213, v15, v139, v177
	v_fma_f32 v214, v8, v140, v178
	v_fma_f32 v215, v9, v141, v179
	v_fma_f32 v216, v10, v142, v180
	v_fma_f32 v217, v11, v143, v181
	v_cvt_pk_bf16_f32 v236, v12, v13
	v_cvt_pk_bf16_f32 v237, v14, v15
	v_cvt_pk_bf16_f32 v238, v8, v9
	v_cvt_pk_bf16_f32 v239, v10, v11
	v_add_u32_e32 v235, 0xffffd400, v233
	s_and_b64 exec, exec, s[10:11]
	global_store_dwordx4 v235, v[236:239], s[42:43]
	s_mov_b64 exec, s[24:25]
	v_fmac_f32_dpp v210, v12, v128 row_shr:1 row_mask:0xf bank_mask:0xf
	v_fmac_f32_dpp v211, v13, v129 row_shr:1 row_mask:0xf bank_mask:0xf
	v_fmac_f32_dpp v212, v14, v130 row_shr:1 row_mask:0xf bank_mask:0xf
	v_fmac_f32_dpp v213, v15, v131 row_shr:1 row_mask:0xf bank_mask:0xf
	v_fmac_f32_dpp v214, v8, v132 row_shr:1 row_mask:0xf bank_mask:0xf
	v_fmac_f32_dpp v215, v9, v133 row_shr:1 row_mask:0xf bank_mask:0xf
	v_fmac_f32_dpp v216, v10, v134 row_shr:1 row_mask:0xf bank_mask:0xf
	v_fmac_f32_dpp v217, v11, v135 row_shr:1 row_mask:0xf bank_mask:0xf
	v_fmac_f32_dpp v210, v12, v88 row_shr:2 row_mask:0xf bank_mask:0xf
	v_fmac_f32_dpp v211, v13, v89 row_shr:2 row_mask:0xf bank_mask:0xf
	v_fmac_f32_dpp v212, v14, v90 row_shr:2 row_mask:0xf bank_mask:0xf
	v_fmac_f32_dpp v213, v15, v91 row_shr:2 row_mask:0xf bank_mask:0xf
	v_fmac_f32_dpp v214, v8, v92 row_shr:2 row_mask:0xf bank_mask:0xf
	v_fmac_f32_dpp v215, v9, v93 row_shr:2 row_mask:0xf bank_mask:0xf
	v_fmac_f32_dpp v216, v10, v94 row_shr:2 row_mask:0xf bank_mask:0xf
	v_fmac_f32_dpp v217, v11, v95 row_shr:2 row_mask:0xf bank_mask:0xf
	v_fmac_f32_dpp v210, v28, v128 row_shl:15 row_mask:0xf bank_mask:0xf
	v_fmac_f32_dpp v211, v29, v129 row_shl:15 row_mask:0xf bank_mask:0xf
	v_fmac_f32_dpp v212, v30, v130 row_shl:15 row_mask:0xf bank_mask:0xf
	v_fmac_f32_dpp v213, v31, v131 row_shl:15 row_mask:0xf bank_mask:0xf
	v_fmac_f32_dpp v214, v24, v132 row_shl:15 row_mask:0xf bank_mask:0xf
	v_fmac_f32_dpp v215, v25, v133 row_shl:15 row_mask:0xf bank_mask:0xf
	v_fmac_f32_dpp v216, v26, v134 row_shl:15 row_mask:0xf bank_mask:0xf
	v_fmac_f32_dpp v217, v27, v135 row_shl:15 row_mask:0xf bank_mask:0xf
	v_fmac_f32_dpp v210, v28, v88 row_shl:14 row_mask:0xf bank_mask:0xf
	v_fmac_f32_dpp v211, v29, v89 row_shl:14 row_mask:0xf bank_mask:0xf
	v_fmac_f32_dpp v212, v30, v90 row_shl:14 row_mask:0xf bank_mask:0xf
	v_fmac_f32_dpp v213, v31, v91 row_shl:14 row_mask:0xf bank_mask:0xf
	v_fmac_f32_dpp v214, v24, v92 row_shl:14 row_mask:0xf bank_mask:0xf
	v_fmac_f32_dpp v215, v25, v93 row_shl:14 row_mask:0xf bank_mask:0xf
	v_fmac_f32_dpp v216, v26, v94 row_shl:14 row_mask:0xf bank_mask:0xf
	v_fmac_f32_dpp v217, v27, v95 row_shl:14 row_mask:0xf bank_mask:0xf
	v_exp_f32_e32 v218, v210
	v_exp_f32_e32 v219, v211
	v_exp_f32_e32 v220, v212
	v_exp_f32_e32 v221, v213
	v_exp_f32_e32 v222, v214
	v_exp_f32_e32 v223, v215
	v_exp_f32_e32 v224, v216
	v_exp_f32_e32 v225, v217
	v_add_f32_e32 v218, 1.0, v218
	v_add_f32_e32 v219, 1.0, v219
	v_add_f32_e32 v220, 1.0, v220
	v_add_f32_e32 v221, 1.0, v221
	v_add_f32_e32 v222, 1.0, v222
	v_add_f32_e32 v223, 1.0, v223
	v_add_f32_e32 v224, 1.0, v224
	v_add_f32_e32 v225, 1.0, v225
	v_rcp_f32_e32 v218, v218
	v_rcp_f32_e32 v219, v219
	v_rcp_f32_e32 v220, v220
	v_rcp_f32_e32 v221, v221
	v_rcp_f32_e32 v222, v222
	v_rcp_f32_e32 v223, v223
	v_rcp_f32_e32 v224, v224
	v_rcp_f32_e32 v225, v225
	v_mul_f32_e32 v4, v4, v209
	v_mul_f32_e32 v5, v5, v209
	v_mul_f32_e32 v6, v6, v209
	v_mul_f32_e32 v7, v7, v209
	v_mul_f32_e32 v0, v0, v209
	v_mul_f32_e32 v1, v1, v209
	v_mul_f32_e32 v2, v2, v209
	v_mul_f32_e32 v3, v3, v209
	v_mul_f32_e32 v210, v210, v218
	v_mul_f32_e32 v211, v211, v219
	v_mul_f32_e32 v212, v212, v220
	v_mul_f32_e32 v213, v213, v221
	v_mul_f32_e32 v214, v214, v222
	v_mul_f32_e32 v215, v215, v223
	v_mul_f32_e32 v216, v216, v224
	v_mul_f32_e32 v217, v217, v225
	v_mul_f32_e32 v4, v210, v4
	v_mul_f32_e32 v5, v211, v5
	v_mul_f32_e32 v6, v212, v6
	v_mul_f32_e32 v7, v213, v7
	v_mul_f32_e32 v0, v214, v0
	v_mul_f32_e32 v1, v215, v1
	v_mul_f32_e32 v2, v216, v2
	v_mul_f32_e32 v3, v217, v3
	v_cvt_pk_bf16_f32 v226, v4, v5
	v_cvt_pk_bf16_f32 v227, v6, v7
	v_cvt_pk_bf16_f32 v228, v0, v1
	v_cvt_pk_bf16_f32 v229, v2, v3
	v_add_u32_e32 v234, 0xf2000, v230
	global_store_dwordx4 v234, v[226:229], s[96:97] nt
